# GU: both halves of the SwiGLU epilogue overlapped with MFMA blocks (ai=0 in the last iteration, ai=1 in the next tile's first iteration when the row panel is unchanged); no alignment barriers on that
# baseline (speedup 1.0000x reference)
; #define PG8_STAGE(bufoff, gbase, voff) do { _Pragma("unroll") for (int _i = 0; _i < 2; ++_i) \
;         __builtin_amdgcn_global_load_lds((const unsigned*)((const char*)(gbase) + (voff)[_i]), (LAS unsigned*)(lds + (bufoff) + ldsw + _i * 8192), 16, 0, 0); } while (0)
; #define PG8_WAIT_V(n) asm volatile("s_waitcnt vmcnt(" #n ")" ::: "memory")
; #define PG8_BAR __builtin_amdgcn_s_barrier()
; template <class Epi, bool ALIGN_EPI>
; __device__ __forceinline__ void gemm_phase(LAS unsigned char* lds, const Gemm g, const StaticOrder& S, const Epi& E, const int tid) {
;     ...
;     unsigned voffA[2], voffB[2];
; #pragma unroll
;     for (int i = 0; i < 2; ++i) { int R, C; stage_rc(tid * 16 + i * 8192, R, C); const int Rb = Epi::PERM ? ((R & ~31) + perm32(R & 31)) : R;
;         voffA[i] = (unsigned)(R * g.lda + C) * 2u; voffB[i] = (unsigned)(Rb * g.ldb + C) * 2u; }
;     const size_t kstep = (size_t)(BK * 2);
;     const size_t hA = (size_t)HALF * g.lda * 2, hB = (size_t)HALF * g.ldb * 2, tA = 2 * hA, tB = 2 * hB;
;     const unsigned ldsw = (unsigned)wid * 1024u;
;     const int aoff = lds_byte(wr * 64 + fr, fq * 8), boff = lds_byte(wc * 32 + fr, fq * 8);
;     ...
;     Unit cur, nxt; int ui = 0;
;     if (!S.next(0, cur)) return;
;     f32x4 acc[2][2][4][2];
; #pragma unroll
;     for (int a = 0; a < 2; ++a)
; #pragma unroll
;         for (int b = 0; b < 2; ++b)
; #pragma unroll
;             for (int m = 0; m < 4; ++m)
; #pragma unroll
;                 for (int n = 0; n < 2; ++n) acc[a][b][m][n] = (f32x4){0.f, 0.f, 0.f, 0.f};
;     bf16x8 At[4][2], B0[2][2], B1[2][2];
;     const char* cA = (const char*)g.A + (size_t)cur.pm * tA + (size_t)cur.pn * g.apn * 2; const char* cB = (const char*)g.Bt + (size_t)cur.pn * tB;
;     PG8_STAGE(PG8_SB(0, 0), cB, voffB); PG8_STAGE(PG8_SB(0, 1), cB + hB, voffB); PG8_STAGE(PG8_SA(0, 0), cA, voffA); PG8_STAGE(PG8_SA(0, 1), cA + hA, voffA);
;     if (wr == 1) PG8_BAR;
;     PG8_WAIT_V(2); PG8_BAR;
;     PG8_STAGE(PG8_SB(1, 0), cB + kstep, voffB); PG8_STAGE(PG8_SA(1, 0), cA + kstep, voffA); PG8_STAGE(PG8_SB(1, 1), cB + hB + kstep, voffB);
;     PG8_WAIT_V(6); PG8_BAR;
.LBB0_297:
	v_lshl_add_u64 v[8:9], v[144:145], 0, v[168:169]
	v_mov_b32_e32 v129, v169
	v_lshl_add_u64 v[10:11], v[144:145], 0, v[128:129]
	v_mov_b32_e32 v133, v169
	s_add_i32 m0, s51, 0x18000
	v_lshl_add_u64 v[8:9], v[8:9], 0, s[92:93]
	v_lshl_add_u64 v[14:15], v[142:143], 0, v[132:133]
	v_mov_b32_e32 v131, v169
	s_waitcnt vmcnt(2)
	s_barrier
	global_load_lds_dwordx4 v[8:9], off
	v_lshl_add_u64 v[8:9], v[10:11], 0, s[92:93]
	s_add_i32 m0, s51, 0x1a000
	s_add_i32 s56, s51, 0x8000
	v_lshl_add_u64 v[16:17], v[142:143], 0, v[130:131]
	global_load_lds_dwordx4 v[8:9], off
	v_lshl_add_u64 v[8:9], v[14:15], 0, s[92:93]
	s_mov_b32 m0, s56
	s_add_i32 s57, s51, 0xa000
	v_lshl_add_u64 v[12:13], v[0:1], 0, v[168:169]
	global_load_lds_dwordx4 v[8:9], off
	v_lshl_add_u64 v[8:9], v[16:17], 0, s[92:93]
	s_mov_b32 m0, s57
	v_lshl_add_u64 v[0:1], v[0:1], 0, v[128:129]
	global_load_lds_dwordx4 v[8:9], off
	s_add_i32 m0, s51, 0x1c000
	v_lshl_add_u64 v[8:9], v[12:13], 0, s[92:93]
	global_load_lds_dwordx4 v[8:9], off
	v_lshl_add_u64 v[0:1], v[0:1], 0, s[92:93]
	s_add_i32 m0, s51, 0x1e000
	v_and_b32_e32 v18, 15, v170
	global_load_lds_dwordx4 v[0:1], off
	v_add_u32_e32 v0, v7, v5
	s_lshr_b32 s55, s1, 6
	v_and_b32_e32 v19, 48, v170
	v_lshlrev_b32_e32 v18, 6, v18
	v_lshlrev_b32_e32 v21, 2, v170
	s_lshl_b32 s9, s9, 12
	v_add_lshl_u32 v0, v0, v6, 1
	v_mov_b32_e32 v1, v169
	v_or_b32_e32 v20, v18, v19
	s_lshl_b32 s10, s10, 13
	v_and_b32_e32 v21, 32, v21
	s_and_b32 s9, s9, 0x3000
	s_waitcnt vmcnt(6)
	s_add_i32 s58, s55, -2
	v_lshl_add_u64 v[134:135], s[94:95], 0, v[0:1]
	v_add_u32_e32 v0, v4, v2
	v_bitop3_b32 v18, v18, v21, v19 bitop3:0x36
	v_bitop3_b32 v19, s10, v20, v21 bitop3:0xf6
	s_cmpk_lt_u32 s8, 0x100
	v_add_lshl_u32 v0, v0, v3, 1
	v_or_b32_e32 v151, s9, v18
	s_cselect_b64 s[42:43], -1, 0
	s_ashr_i32 s59, s6, 31
	s_mov_b32 s39, s95
	v_lshl_add_u64 v[136:137], s[94:95], 0, v[0:1]
	s_mov_b32 s60, 0
	v_add_u32_e32 v153, 0, v19
	s_barrier
	v_mov_b32_e32 v254, -1
	s_mov_b32 s101, 0
	s_branch .LBB0_300

;     __device__ bool next(int i, Unit& u) const {
;         const long L = (long)i * G + c; if (L >= nwg) return false;
;         int wgid = (int)L; { const int q = nwg / NXCD, r = nwg % NXCD, xcd = wgid % NXCD, off = wgid / NXCD; wgid = (xcd < r ? xcd * (q + 1) : r * (q + 1) + (xcd - r) * q) + off; }
;         const int nig = WGM * nN, gid = wgid / nig, fm = gid * WGM, gsz = (nM - fm) < WGM ? (nM - fm) : WGM;
;         u.pm = fm + ((wgid % nig) % gsz); u.pn = (wgid % nig) / gsz; return true;
;     }
; template <class Epi, bool ALIGN_EPI>
; __device__ __forceinline__ void gemm_phase(LAS unsigned char* lds, const Gemm g, const StaticOrder& S, const Epi& E, const int tid) {
;     ...
;         const bool has_next = S.next(ui + 1, nxt);
;         const char* nA = has_next ? (const char*)g.A + (size_t)nxt.pm * tA + (size_t)nxt.pn * g.apn * 2 : cA; const char* nB = has_next ? (const char*)g.Bt + (size_t)nxt.pn * tB : cB;
.LBB0_300:
	s_add_i32 s60, s60, 1
	s_mul_i32 s8, s60, s59
	s_mul_hi_u32 s9, s60, s6
	s_add_i32 s9, s9, s8
	s_mul_i32 s8, s60, s6
	s_add_u32 s8, s8, s0
	s_addc_u32 s9, s9, s47
	v_mov_b64_e32 v[224:225], s[38:39]
	v_cmp_ge_i64_e32 vcc, s[8:9], v[224:225]
	v_cmp_lt_i64_e64 s[10:11], s[8:9], v[224:225]
	s_cbranch_vccnz .LBB0_302
	s_ashr_i32 s9, s8, 31
	s_lshr_b32 s9, s9, 29
	s_add_i32 s9, s8, s9
	s_ashr_i32 s61, s9, 3
	s_and_b32 s9, s9, -8
	s_sub_i32 s8, s8, s9
	s_cmp_lt_i32 s8, 0
	s_cselect_b32 s9, s48, s46
	s_mul_i32 s8, s9, s8
	s_add_i32 s8, s8, s61
	s_abs_i32 s61, s8
	s_mul_hi_u32 s62, s61, s50
	s_mul_i32 s65, s62, s49
	s_sub_i32 s61, s61, s65
	s_ashr_i32 s9, s8, 31
	s_add_i32 s65, s62, 1
	s_sub_i32 s66, s61, s49
	s_cmp_ge_u32 s61, s49
	s_cselect_b32 s62, s65, s62
	s_cselect_b32 s61, s66, s61
	s_add_i32 s65, s62, 1
	s_cmp_ge_u32 s61, s49
	s_cselect_b32 s61, s65, s62
	s_xor_b32 s61, s61, s9
	s_sub_i32 s9, s61, s9
	s_lshl_b32 s62, s9, 3
	s_sub_i32 s61, 0x80, s62
	s_min_i32 s65, s61, 8
	s_abs_i32 s61, s65
	v_cvt_f32_u32_e32 v224, s61
	s_sub_i32 s67, 0, s61
	s_mul_i32 s9, s9, s49
	s_sub_i32 s8, s8, s9
	v_rcp_iflag_f32_e32 v224, v224
	s_abs_i32 s66, s8
	s_xor_b32 s9, s8, s65
	s_ashr_i32 s9, s9, 31
	v_mul_f32_e32 v224, 0x4f7ffffe, v224
	v_cvt_u32_f32_e32 v224, v224
	s_mov_b64 s[70:71], s[90:91]
	v_readfirstlane_b32 s68, v224
	s_mul_i32 s67, s67, s68
	s_mul_hi_u32 s67, s68, s67
	s_add_i32 s68, s68, s67
	s_mul_hi_u32 s67, s66, s68
	s_mul_i32 s68, s67, s61
	s_sub_i32 s66, s66, s68
	s_add_i32 s68, s67, 1
	s_sub_i32 s69, s66, s61
	s_cmp_ge_u32 s66, s61
	s_cselect_b32 s67, s68, s67
	s_cselect_b32 s66, s69, s66
	s_add_i32 s68, s67, 1
	s_cmp_ge_u32 s66, s61
	s_cselect_b32 s61, s68, s67
	s_xor_b32 s61, s61, s9
	s_sub_i32 s61, s61, s9
	s_mul_i32 s9, s61, s65
	s_sub_i32 s8, s8, s9
	s_add_i32 s62, s8, s62
.LBB0_302:
	s_nop 0
	v_cndmask_b32_e64 v224, 0, 1, s[10:11]
	v_cmp_ne_u32_e64 s[8:9], 1, v224
	s_andn2_b64 vcc, exec, s[10:11]
	v_mov_b64_e32 v[138:139], v[142:143]
	s_cbranch_vccnz .LBB0_304
	s_ashr_i32 s10, s62, 31
	s_mul_hi_u32 s11, s14, s62
	s_mul_i32 s10, s14, s10
	s_add_i32 s10, s11, s10
	s_mul_i32 s11, s15, s62
	s_add_i32 s11, s10, s11
	s_mul_i32 s10, s14, s62
	v_lshl_add_u64 v[224:225], v[174:175], 0, s[10:11]
	s_ashr_i32 s10, s61, 31
	s_mul_hi_u32 s11, s16, s61
	s_mul_i32 s10, s16, s10
	s_add_i32 s10, s11, s10
	s_mul_i32 s11, s17, s61
	s_add_i32 s11, s10, s11
	s_mul_i32 s10, s16, s61
	v_lshl_add_u64 v[138:139], v[224:225], 0, s[10:11]

; __device__ __forceinline__ unsigned cvt_pk_bf16(float lo, float hi) { unsigned r; asm volatile("v_cvt_pk_bf16_f32 %0, %1, %2" : "=v"(r) : "v"(lo), "v"(hi)); return r; }
; __device__ __forceinline__ float siluf_(float x) { return x * sigmoidf_(x); }
; #define PG8_STAGE(bufoff, gbase, voff) do { _Pragma("unroll") for (int _i = 0; _i < 2; ++_i) \
;         __builtin_amdgcn_global_load_lds((const unsigned*)((const char*)(gbase) + (voff)[_i]), (LAS unsigned*)(lds + (bufoff) + ldsw + _i * 8192), 16, 0, 0); } while (0)
; #define PG8_LDA(dst, b, h) do { _Pragma("unroll") for (int m = 0; m < 4; ++m) _Pragma("unroll") for (int k = 0; k < 2; ++k) dst[m][k] = *(const LAS bf16x8*)(lds + PG8_SA(b, h) + aoff + m * 2048 + k * 1024); } while (0)
;     __device__ __forceinline__ void operator()(const f32x4 (&acc)[2][2][4][2], const Unit& u, int wr, int wc, int fr, int fq) const {
;         const int row0 = u.pm * BM + wr * 64 + fr, col0 = u.pn * HALF + wc * 32 + 8 * fq;
;         float rsv[2][4]; load_rstd(rsv, ssq, row0);
; #pragma unroll
;         for (int ai = 0; ai < 2; ++ai)
; #pragma unroll
;             for (int m = 0; m < 4; ++m) { const int row = row0 + ai * HALF + m * 16; bf16_t* rowp = O + (size_t)row * ldc + col0; const float rs = rsv[ai][m];
;                 f32x4 v0, v1;
; #pragma unroll
;                 for (int j = 0; j < 4; ++j) { v0[j] = siluf_(acc[ai][0][m][0][j] * rs) * (acc[ai][1][m][0][j] * rs); v1[j] = siluf_(acc[ai][0][m][1][j] * rs) * (acc[ai][1][m][1][j] * rs); }
;                 u32x4 w; w.x = cvt_pk_bf16(v0[0], v0[1]); w.y = cvt_pk_bf16(v0[2], v0[3]); w.z = cvt_pk_bf16(v1[0], v1[1]); w.w = cvt_pk_bf16(v1[2], v1[3]);
;                 *(u32x4*)rowp = w; }
; template <class Epi, bool ALIGN_EPI>
; __device__ __forceinline__ void gemm_phase(LAS unsigned char* lds, const Gemm g, const StaticOrder& S, const Epi& E, const int tid) {
;     ...
;             PG8_LDB(B0, 0, 0); PG8_LDB(B1, 0, 1); PG8_SCHED; PG8_LDA(At, 0, 0); PG8_STAGE(PG8_SA(1, 1), a1 + hA, voffA);
;             PG8_WAIT_V(8); PG8_WAIT_L(0); PG8_BAR; PG8_MMA(0, 0, At, B0); PG8_MMA(0, 1, At, B1); PG8_BAR; PG8_SCHED;
;             PG8_LDA(At, 0, 1); PG8_STAGE(PG8_SB(0, 0), b2, voffB); PG8_STAGE(PG8_SB(0, 1), b2 + hB, voffB); PG8_STAGE(PG8_SA(0, 0), a2, voffA);
;             PG8_WAIT_V(8); PG8_WAIT_L(0); PG8_BAR; PG8_MMA(1, 0, At, B0); PG8_MMA(1, 1, At, B1); PG8_BAR; PG8_SCHED;
.Lgu_rs_ok:
	s_cmp_eq_u32 s101, 0
	s_cbranch_scc1 .Lgu_first
.Lgu_first_epi:
	s_add_i32 s11, s10, 2
	s_cmp_eq_u32 s58, s10
	v_lshl_add_u64 v[146:147], v[142:143], 0, s[92:93]
	s_cselect_b64 vcc, -1, 0
	v_add_u32_e32 v150, s33, v151
	s_add_i32 s10, 0, 0x14000
	v_cndmask_b32_e32 v167, v147, v139, vcc
	v_cndmask_b32_e32 v166, v146, v138, vcc
	ds_read_b128 v[146:149], v150
	ds_read_b128 v[154:157], v150 offset:1024
	ds_read_b128 v[158:161], v150 offset:2048
	ds_read_b128 v[162:165], v150 offset:3072
	v_add_u32_e32 v150, s10, v151
	ds_read_b128 v[176:179], v150
	ds_read_b128 v[180:183], v150 offset:1024
	ds_read_b128 v[184:187], v150 offset:2048
	ds_read_b128 v[188:191], v150 offset:3072
	v_cndmask_b32_e32 v221, v145, v141, vcc
	v_cndmask_b32_e32 v220, v144, v140, vcc
	v_lshl_add_u64 v[226:227], v[142:143], 0, v[134:135]
	s_add_i32 m0, s51, 0xc000
	ds_read_b128 v[192:195], v153
	ds_read_b128 v[196:199], v153 offset:1024
	ds_read_b128 v[200:203], v153 offset:2048
	ds_read_b128 v[204:207], v153 offset:3072
	ds_read_b128 v[208:211], v153 offset:4096
	ds_read_b128 v[212:215], v153 offset:5120
	ds_read_b128 v[216:219], v153 offset:6144
	ds_read_b128 v[240:243], v153 offset:7168
	global_load_lds_dwordx4 v[226:227], off
	v_lshl_add_u64 v[226:227], v[142:143], 0, v[136:137]
	s_add_i32 m0, s51, 0xe000
	s_nop 0
	global_load_lds_dwordx4 v[226:227], off
	s_waitcnt vmcnt(8)
	s_waitcnt lgkmcnt(0)
	s_barrier
	s_setprio 1
	s_waitcnt lgkmcnt(0)
	v_mfma_f32_16x16x32_bf16 v[120:123], v[146:149], v[192:195], 0
	s_lshl_b32 s98, s28, 5
	s_mov_b32 s99, 0
	s_mov_b32 s100, 0xbfb8aa3b
	s_mov_b32 s101, 0xbfb8aa3b
	v_mul_f32_e32 v56, v238, v56
	v_mul_f32_e32 v57, v238, v57
	v_mul_f32_e32 v58, v238, v58
	v_mul_f32_e32 v59, v238, v59
	v_mul_f32_e32 v60, v238, v60
	v_mul_f32_e32 v61, v238, v61
	v_mfma_f32_16x16x32_bf16 v[112:115], v[158:161], v[192:195], 0
	v_mul_f32_e32 v62, v238, v62
	v_mul_f32_e32 v63, v238, v63
	v_mul_f32_e32 v224, s100, v56
	v_mul_f32_e32 v225, s101, v57
	v_mul_f32_e32 v228, s100, v58
	v_mul_f32_e32 v229, s101, v59
	v_exp_f32_e32 v224, v224
	v_exp_f32_e32 v225, v225
	v_exp_f32_e32 v228, v228
	v_exp_f32_e32 v229, v229
	v_mfma_f32_16x16x32_bf16 v[104:107], v[146:149], v[200:203], 0
	v_add_f32_e32 v224, 1.0, v224
	v_add_f32_e32 v225, 1.0, v225
	v_add_f32_e32 v228, 1.0, v228
	v_add_f32_e32 v229, 1.0, v229
	v_rcp_f32_e32 v224, v224
	v_rcp_f32_e32 v225, v225
	v_rcp_f32_e32 v228, v228
	v_rcp_f32_e32 v229, v229
	v_nop
	v_mul_f32_e32 v56, v224, v56
	v_mfma_f32_16x16x32_bf16 v[96:99], v[158:161], v[200:203], 0
	v_mul_f32_e32 v57, v225, v57
	v_mul_f32_e32 v58, v228, v58
	v_mul_f32_e32 v59, v229, v59
	v_mul_f32_e32 v56, v60, v56
	v_mul_f32_e32 v57, v61, v57
	v_mul_f32_e32 v58, v62, v58
	v_mul_f32_e32 v59, v63, v59
	v_mul_f32_e32 v48, v238, v48
	v_mul_f32_e32 v49, v238, v49
	v_mul_f32_e32 v50, v238, v50
	v_mfma_f32_16x16x32_bf16 v[88:91], v[146:149], v[208:211], 0
	v_mul_f32_e32 v51, v238, v51
	v_mul_f32_e32 v52, v238, v52
	v_mul_f32_e32 v53, v238, v53
	v_mul_f32_e32 v54, v238, v54
	v_mul_f32_e32 v55, v238, v55
	v_mul_f32_e32 v224, s100, v48
	v_mul_f32_e32 v225, s101, v49
	v_mul_f32_e32 v228, s100, v50
	v_mul_f32_e32 v229, s101, v51
	v_exp_f32_e32 v224, v224
	v_mfma_f32_16x16x32_bf16 v[80:83], v[158:161], v[208:211], 0
	v_exp_f32_e32 v225, v225
	v_exp_f32_e32 v228, v228
	v_exp_f32_e32 v229, v229
	v_add_f32_e32 v224, 1.0, v224
	v_add_f32_e32 v225, 1.0, v225
	v_add_f32_e32 v228, 1.0, v228
	v_add_f32_e32 v229, 1.0, v229
	v_rcp_f32_e32 v224, v224
	v_rcp_f32_e32 v225, v225
	v_rcp_f32_e32 v228, v228
	v_mfma_f32_16x16x32_bf16 v[72:75], v[146:149], v[216:219], 0
	v_rcp_f32_e32 v229, v229
	v_nop
	v_mul_f32_e32 v48, v224, v48
	v_mul_f32_e32 v49, v225, v49
	v_mul_f32_e32 v50, v228, v50
	v_mul_f32_e32 v51, v229, v51
	v_mul_f32_e32 v48, v52, v48
	v_mul_f32_e32 v49, v53, v49
	v_mul_f32_e32 v50, v54, v50
	v_mul_f32_e32 v51, v55, v51
	v_mfma_f32_16x16x32_bf16 v[64:67], v[158:161], v[216:219], 0
	v_cvt_pk_bf16_f32 v56, v56, v57
	v_cvt_pk_bf16_f32 v57, v58, v59
	v_cvt_pk_bf16_f32 v58, v48, v49
	v_cvt_pk_bf16_f32 v59, v50, v51
	global_store_dwordx4 v[232:233], v[56:59], off
	v_lshl_add_u64 v[232:233], v[232:233], 0, s[98:99]
	v_mul_f32_e32 v40, v239, v40
	v_mul_f32_e32 v41, v239, v41
	v_mul_f32_e32 v42, v239, v42
	v_mul_f32_e32 v43, v239, v43
	v_mfma_f32_16x16x32_bf16 v[120:123], v[154:157], v[196:199], v[120:123]
	v_mul_f32_e32 v44, v239, v44
	v_mul_f32_e32 v45, v239, v45
	v_mul_f32_e32 v46, v239, v46
	v_mul_f32_e32 v47, v239, v47
	v_mul_f32_e32 v224, s100, v40
	v_mul_f32_e32 v225, s101, v41
	v_mul_f32_e32 v228, s100, v42
	v_mul_f32_e32 v229, s101, v43
	v_exp_f32_e32 v224, v224
	v_exp_f32_e32 v225, v225
	v_mfma_f32_16x16x32_bf16 v[112:115], v[162:165], v[196:199], v[112:115]
	v_exp_f32_e32 v228, v228
	v_exp_f32_e32 v229, v229
	v_add_f32_e32 v224, 1.0, v224
	v_add_f32_e32 v225, 1.0, v225
	v_add_f32_e32 v228, 1.0, v228
	v_add_f32_e32 v229, 1.0, v229
	v_rcp_f32_e32 v224, v224
	v_rcp_f32_e32 v225, v225
	v_rcp_f32_e32 v228, v228
	v_rcp_f32_e32 v229, v229
	v_mfma_f32_16x16x32_bf16 v[104:107], v[154:157], v[204:207], v[104:107]
	v_nop
	v_mul_f32_e32 v40, v224, v40
	v_mul_f32_e32 v41, v225, v41
	v_mul_f32_e32 v42, v228, v42
	v_mul_f32_e32 v43, v229, v43
	v_mul_f32_e32 v40, v44, v40
	v_mul_f32_e32 v41, v45, v41
	v_mul_f32_e32 v42, v46, v42
	v_mul_f32_e32 v43, v47, v43
	v_mul_f32_e32 v32, v239, v32
	v_mfma_f32_16x16x32_bf16 v[96:99], v[162:165], v[204:207], v[96:99]
	v_mul_f32_e32 v33, v239, v33
	v_mul_f32_e32 v34, v239, v34
	v_mul_f32_e32 v35, v239, v35
	v_mul_f32_e32 v36, v239, v36
	v_mul_f32_e32 v37, v239, v37
	v_mul_f32_e32 v38, v239, v38
	v_mul_f32_e32 v39, v239, v39
	v_mul_f32_e32 v224, s100, v32
; __device__ __forceinline__ unsigned cvt_pk_bf16(float lo, float hi) { unsigned r; asm volatile("v_cvt_pk_bf16_f32 %0, %1, %2" : "=v"(r) : "v"(lo), "v"(hi)); return r; }
; __device__ __forceinline__ float siluf_(float x) { return x * sigmoidf_(x); }
;     __device__ __forceinline__ void operator()(const f32x4 (&acc)[2][2][4][2], const Unit& u, int wr, int wc, int fr, int fq) const {
;         const int row0 = u.pm * BM + wr * 64 + fr, col0 = u.pn * HALF + wc * 32 + 8 * fq;
;         float rsv[2][4]; load_rstd(rsv, ssq, row0);
; #pragma unroll
;         for (int ai = 0; ai < 2; ++ai)
; #pragma unroll
;             for (int m = 0; m < 4; ++m) { const int row = row0 + ai * HALF + m * 16; bf16_t* rowp = O + (size_t)row * ldc + col0; const float rs = rsv[ai][m];
;                 f32x4 v0, v1;
; #pragma unroll
;                 for (int j = 0; j < 4; ++j) { v0[j] = siluf_(acc[ai][0][m][0][j] * rs) * (acc[ai][1][m][0][j] * rs); v1[j] = siluf_(acc[ai][0][m][1][j] * rs) * (acc[ai][1][m][1][j] * rs); }
;                 u32x4 w; w.x = cvt_pk_bf16(v0[0], v0[1]); w.y = cvt_pk_bf16(v0[2], v0[3]); w.z = cvt_pk_bf16(v1[0], v1[1]); w.w = cvt_pk_bf16(v1[2], v1[3]);
;                 *(u32x4*)rowp = w; }
	v_mul_f32_e32 v225, s101, v33
	v_mul_f32_e32 v228, s100, v34
	v_mfma_f32_16x16x32_bf16 v[88:91], v[154:157], v[212:215], v[88:91]
	v_mul_f32_e32 v229, s101, v35
	v_exp_f32_e32 v224, v224
	v_exp_f32_e32 v225, v225
	v_exp_f32_e32 v228, v228
	v_exp_f32_e32 v229, v229
	v_add_f32_e32 v224, 1.0, v224
	v_add_f32_e32 v225, 1.0, v225
	v_add_f32_e32 v228, 1.0, v228
	v_add_f32_e32 v229, 1.0, v229
	v_rcp_f32_e32 v224, v224
	v_mfma_f32_16x16x32_bf16 v[80:83], v[162:165], v[212:215], v[80:83]
	v_rcp_f32_e32 v225, v225
	v_rcp_f32_e32 v228, v228
	v_rcp_f32_e32 v229, v229
	v_nop
	v_mul_f32_e32 v32, v224, v32
	v_mul_f32_e32 v33, v225, v33
	v_mul_f32_e32 v34, v228, v34
	v_mul_f32_e32 v35, v229, v35
	v_mul_f32_e32 v32, v36, v32
	v_mul_f32_e32 v33, v37, v33
	v_mfma_f32_16x16x32_bf16 v[72:75], v[154:157], v[240:243], v[72:75]
	v_mul_f32_e32 v34, v38, v34
	v_mul_f32_e32 v35, v39, v35
	v_cvt_pk_bf16_f32 v40, v40, v41
	v_cvt_pk_bf16_f32 v41, v42, v43
	v_cvt_pk_bf16_f32 v42, v32, v33
	v_cvt_pk_bf16_f32 v43, v34, v35
	global_store_dwordx4 v[232:233], v[40:43], off
	v_lshl_add_u64 v[232:233], v[232:233], 0, s[98:99]
	v_mul_f32_e32 v24, v230, v24
	v_mul_f32_e32 v25, v230, v25
	v_mfma_f32_16x16x32_bf16 v[64:67], v[162:165], v[240:243], v[64:67]
	v_mul_f32_e32 v26, v230, v26
	v_mul_f32_e32 v27, v230, v27
	v_mul_f32_e32 v28, v230, v28
	v_mul_f32_e32 v29, v230, v29
	v_mul_f32_e32 v30, v230, v30
	v_mul_f32_e32 v31, v230, v31
	v_mul_f32_e32 v224, s100, v24
	v_mul_f32_e32 v225, s101, v25
	v_mul_f32_e32 v228, s100, v26
	v_mul_f32_e32 v229, s101, v27
	s_setprio 0
	s_setprio 1
	v_mfma_f32_16x16x32_bf16 v[124:127], v[176:179], v[192:195], 0
	v_exp_f32_e32 v224, v224
	v_exp_f32_e32 v225, v225
	v_exp_f32_e32 v228, v228
	v_exp_f32_e32 v229, v229
	v_add_f32_e32 v224, 1.0, v224
	v_add_f32_e32 v225, 1.0, v225
	v_add_f32_e32 v228, 1.0, v228
	v_add_f32_e32 v229, 1.0, v229
	v_rcp_f32_e32 v224, v224
	v_rcp_f32_e32 v225, v225
	v_mfma_f32_16x16x32_bf16 v[116:119], v[184:187], v[192:195], 0
	v_rcp_f32_e32 v228, v228
	v_rcp_f32_e32 v229, v229
	v_nop
	v_mul_f32_e32 v24, v224, v24
	v_mul_f32_e32 v25, v225, v25
	v_mul_f32_e32 v26, v228, v26
	v_mul_f32_e32 v27, v229, v27
	v_mul_f32_e32 v24, v28, v24
	v_mul_f32_e32 v25, v29, v25
	v_mul_f32_e32 v26, v30, v26
	v_mfma_f32_16x16x32_bf16 v[108:111], v[176:179], v[200:203], 0
	v_mul_f32_e32 v27, v31, v27
	v_mul_f32_e32 v16, v230, v16
	v_mul_f32_e32 v17, v230, v17
	v_mul_f32_e32 v18, v230, v18
	v_mul_f32_e32 v19, v230, v19
	v_mul_f32_e32 v20, v230, v20
	v_mul_f32_e32 v21, v230, v21
	v_mul_f32_e32 v22, v230, v22
	v_mul_f32_e32 v23, v230, v23
	v_mul_f32_e32 v224, s100, v16
	v_mfma_f32_16x16x32_bf16 v[100:103], v[184:187], v[200:203], 0
	v_mul_f32_e32 v225, s101, v17
	v_mul_f32_e32 v228, s100, v18
	v_mul_f32_e32 v229, s101, v19
	v_exp_f32_e32 v224, v224
	v_exp_f32_e32 v225, v225
	v_exp_f32_e32 v228, v228
	v_exp_f32_e32 v229, v229
	v_add_f32_e32 v224, 1.0, v224
	v_add_f32_e32 v225, 1.0, v225
	v_add_f32_e32 v228, 1.0, v228
	v_mfma_f32_16x16x32_bf16 v[92:95], v[176:179], v[208:211], 0
	v_add_f32_e32 v229, 1.0, v229
	v_rcp_f32_e32 v224, v224
	v_rcp_f32_e32 v225, v225
	v_rcp_f32_e32 v228, v228
	v_rcp_f32_e32 v229, v229
	v_nop
	v_mul_f32_e32 v16, v224, v16
	v_mul_f32_e32 v17, v225, v17
	v_mul_f32_e32 v18, v228, v18
	v_mul_f32_e32 v19, v229, v19
	v_mfma_f32_16x16x32_bf16 v[84:87], v[184:187], v[208:211], 0
	v_mul_f32_e32 v16, v20, v16
	v_mul_f32_e32 v17, v21, v17
	v_mul_f32_e32 v18, v22, v18
	v_mul_f32_e32 v19, v23, v19
	v_cvt_pk_bf16_f32 v24, v24, v25
	v_cvt_pk_bf16_f32 v25, v26, v27
	v_cvt_pk_bf16_f32 v26, v16, v17
	v_cvt_pk_bf16_f32 v27, v18, v19
	global_store_dwordx4 v[232:233], v[24:27], off
	v_lshl_add_u64 v[232:233], v[232:233], 0, s[98:99]
	v_mfma_f32_16x16x32_bf16 v[76:79], v[176:179], v[216:219], 0
	v_mul_f32_e32 v8, v231, v8
	v_mul_f32_e32 v9, v231, v9
	v_mul_f32_e32 v10, v231, v10
	v_mul_f32_e32 v11, v231, v11
	v_mul_f32_e32 v12, v231, v12
	v_mul_f32_e32 v13, v231, v13
	v_mul_f32_e32 v14, v231, v14
	v_mul_f32_e32 v15, v231, v15
	v_mul_f32_e32 v224, s100, v8
	v_mul_f32_e32 v225, s101, v9
	v_mfma_f32_16x16x32_bf16 v[68:71], v[184:187], v[216:219], 0
	v_mul_f32_e32 v228, s100, v10
	v_mul_f32_e32 v229, s101, v11
	v_exp_f32_e32 v224, v224
	v_exp_f32_e32 v225, v225
	v_exp_f32_e32 v228, v228
	v_exp_f32_e32 v229, v229
	v_add_f32_e32 v224, 1.0, v224
	v_add_f32_e32 v225, 1.0, v225
	v_add_f32_e32 v228, 1.0, v228
	v_add_f32_e32 v229, 1.0, v229
	v_mfma_f32_16x16x32_bf16 v[124:127], v[180:183], v[196:199], v[124:127]
	v_rcp_f32_e32 v224, v224
	v_rcp_f32_e32 v225, v225
	v_rcp_f32_e32 v228, v228
	v_rcp_f32_e32 v229, v229
	v_nop
	v_mul_f32_e32 v8, v224, v8
	v_mul_f32_e32 v9, v225, v9
	v_mul_f32_e32 v10, v228, v10
	v_mul_f32_e32 v11, v229, v11
	v_mul_f32_e32 v8, v12, v8
	v_mfma_f32_16x16x32_bf16 v[116:119], v[188:191], v[196:199], v[116:119]
	v_mul_f32_e32 v9, v13, v9
	v_mul_f32_e32 v10, v14, v10
	v_mul_f32_e32 v11, v15, v11
	v_mul_f32_e32 v4, v231, v4
	v_mul_f32_e32 v5, v231, v5
	v_mul_f32_e32 v6, v231, v6
	v_mul_f32_e32 v7, v231, v7
	v_mul_f32_e32 v0, v231, v0
	v_mul_f32_e32 v1, v231, v1
	v_mul_f32_e32 v2, v231, v2
	v_mfma_f32_16x16x32_bf16 v[108:111], v[180:183], v[204:207], v[108:111]
	v_mul_f32_e32 v3, v231, v3
	v_mul_f32_e32 v224, s100, v4
	v_mul_f32_e32 v225, s101, v5
	v_mul_f32_e32 v228, s100, v6
	v_mul_f32_e32 v229, s101, v7
	v_exp_f32_e32 v224, v224
	v_exp_f32_e32 v225, v225
	v_exp_f32_e32 v228, v228
	v_exp_f32_e32 v229, v229
	v_add_f32_e32 v224, 1.0, v224
	v_mfma_f32_16x16x32_bf16 v[100:103], v[188:191], v[204:207], v[100:103]
	v_add_f32_e32 v225, 1.0, v225
	v_add_f32_e32 v228, 1.0, v228
	v_add_f32_e32 v229, 1.0, v229
	v_rcp_f32_e32 v224, v224
	v_rcp_f32_e32 v225, v225
	v_rcp_f32_e32 v228, v228
	v_rcp_f32_e32 v229, v229
	v_nop
	v_mul_f32_e32 v4, v224, v4
	v_mul_f32_e32 v5, v225, v5
	v_mfma_f32_16x16x32_bf16 v[92:95], v[180:183], v[212:215], v[92:95]
	v_mul_f32_e32 v6, v228, v6
	v_mul_f32_e32 v7, v229, v7
	v_mul_f32_e32 v4, v0, v4
	v_mul_f32_e32 v5, v1, v5
	v_mul_f32_e32 v6, v2, v6
	v_mul_f32_e32 v7, v3, v7
	v_cvt_pk_bf16_f32 v8, v8, v9
	v_cvt_pk_bf16_f32 v9, v10, v11
	v_cvt_pk_bf16_f32 v10, v4, v5
	v_cvt_pk_bf16_f32 v11, v6, v7
	v_mfma_f32_16x16x32_bf16 v[84:87], v[188:191], v[212:215], v[84:87]
	global_store_dwordx4 v[232:233], v[8:11], off
	v_mfma_f32_16x16x32_bf16 v[76:79], v[180:183], v[240:243], v[76:79]
	v_mfma_f32_16x16x32_bf16 v[68:71], v[188:191], v[240:243], v[68:71]
	s_setprio 0
	s_barrier
; #define PG8_STAGE(bufoff, gbase, voff) do { _Pragma("unroll") for (int _i = 0; _i < 2; ++_i) \
;         __builtin_amdgcn_global_load_lds((const unsigned*)((const char*)(gbase) + (voff)[_i]), (LAS unsigned*)(lds + (bufoff) + ldsw + _i * 8192), 16, 0, 0); } while (0)
; #define PG8_LDA(dst, b, h) do { _Pragma("unroll") for (int m = 0; m < 4; ++m) _Pragma("unroll") for (int k = 0; k < 2; ++k) dst[m][k] = *(const LAS bf16x8*)(lds + PG8_SA(b, h) + aoff + m * 2048 + k * 1024); } while (0)
; #define PG8_LDB(dst, b, h) do { _Pragma("unroll") for (int n = 0; n < 2; ++n) _Pragma("unroll") for (int k = 0; k < 2; ++k) dst[n][k] = *(const LAS bf16x8*)(lds + PG8_SB(b, h) + boff + n * 2048 + k * 1024); } while (0)
; #define PG8_MMA(ai, bj, At, Bt) do { __builtin_amdgcn_s_setprio(1); _Pragma("unroll") for (int k = 0; k < 2; ++k) _Pragma("unroll") for (int m = 0; m < 4; ++m) _Pragma("unroll") for (int n = 0; n < 2; ++n) \
;         acc[ai][bj][m][n] = __builtin_amdgcn_mfma_f32_16x16x32_bf16(Bt[n][k], At[m][k], acc[ai][bj][m][n], 0, 0, 0); __builtin_amdgcn_s_setprio(0); } while (0)
; #define PG8_WAIT_V(n) asm volatile("s_waitcnt vmcnt(" #n ")" ::: "memory")
; #define PG8_WAIT_L(n) asm volatile("s_waitcnt lgkmcnt(" #n ")" ::: "memory")
; #define PG8_BAR __builtin_amdgcn_s_barrier()
; #define PG8_SCHED __builtin_amdgcn_sched_barrier(0)
; template <class Epi, bool ALIGN_EPI>
; __device__ __forceinline__ void gemm_phase(LAS unsigned char* lds, const Gemm g, const StaticOrder& S, const Epi& E, const int tid) {
;     ...
;             PG8_LDA(At, 0, 1); PG8_STAGE(PG8_SB(0, 0), b2, voffB); PG8_STAGE(PG8_SB(0, 1), b2 + hB, voffB); PG8_STAGE(PG8_SA(0, 0), a2, voffA);
;             PG8_WAIT_V(8); PG8_WAIT_L(0); PG8_BAR; PG8_MMA(1, 0, At, B0); PG8_MMA(1, 1, At, B1); PG8_BAR; PG8_SCHED;
;             PG8_LDB(B0, 1, 0); PG8_LDB(B1, 1, 1); PG8_SCHED; PG8_LDA(At, 1, 0); PG8_STAGE(PG8_SA(0, 1), a2 + hA, voffA);
	s_add_i32 s65, s33, s45
	v_lshl_add_u64 v[226:227], v[220:221], 0, v[168:169]
	s_mov_b32 m0, s65
	ds_read_b128 v[192:195], v153 offset:16384
	ds_read_b128 v[196:199], v153 offset:17408
	ds_read_b128 v[200:203], v153 offset:18432
	ds_read_b128 v[204:207], v153 offset:19456
	ds_read_b128 v[208:211], v153 offset:20480
	ds_read_b128 v[212:215], v153 offset:21504
	ds_read_b128 v[216:219], v153 offset:22528
	ds_read_b128 v[240:243], v153 offset:23552
	global_load_lds_dwordx4 v[226:227], off
	v_lshl_add_u64 v[244:245], v[220:221], 0, v[128:129]
	s_add_i32 m0, s65, 0x2000
	v_lshl_add_u64 v[220:221], v[220:221], 0, s[12:13]
	s_add_i32 s10, s10, s45
	global_load_lds_dwordx4 v[244:245], off
	v_lshl_add_u64 v[246:247], v[220:221], 0, v[168:169]
	s_mov_b32 m0, s10
	v_lshl_add_u64 v[220:221], v[220:221], 0, v[128:129]
	global_load_lds_dwordx4 v[246:247], off
	s_add_i32 m0, s10, 0x2000
	v_lshl_add_u64 v[248:249], v[166:167], 0, v[132:133]
	global_load_lds_dwordx4 v[220:221], off
	s_mov_b32 m0, s51
	v_lshl_add_u64 v[250:251], v[166:167], 0, v[130:131]
	global_load_lds_dwordx4 v[248:249], off
	s_mov_b32 m0, s52
	s_nop 0
	global_load_lds_dwordx4 v[250:251], off
	s_waitcnt vmcnt(8)
	s_waitcnt lgkmcnt(0)
	s_barrier
	s_setprio 1
	s_waitcnt lgkmcnt(0)
	v_mfma_f32_16x16x32_bf16 v[56:59], v[146:149], v[192:195], 0
	v_mfma_f32_16x16x32_bf16 v[48:51], v[158:161], v[192:195], 0
	v_mfma_f32_16x16x32_bf16 v[40:43], v[146:149], v[200:203], 0
	v_mfma_f32_16x16x32_bf16 v[32:35], v[158:161], v[200:203], 0
	v_mfma_f32_16x16x32_bf16 v[24:27], v[146:149], v[208:211], 0
	v_mfma_f32_16x16x32_bf16 v[16:19], v[158:161], v[208:211], 0
	v_mfma_f32_16x16x32_bf16 v[8:11], v[146:149], v[216:219], 0
	v_mfma_f32_16x16x32_bf16 v[4:7], v[158:161], v[216:219], 0
	v_mfma_f32_16x16x32_bf16 v[56:59], v[154:157], v[196:199], v[56:59]
	v_mfma_f32_16x16x32_bf16 v[48:51], v[162:165], v[196:199], v[48:51]
	v_mfma_f32_16x16x32_bf16 v[40:43], v[154:157], v[204:207], v[40:43]
	v_mfma_f32_16x16x32_bf16 v[32:35], v[162:165], v[204:207], v[32:35]
	v_mfma_f32_16x16x32_bf16 v[24:27], v[154:157], v[212:215], v[24:27]
	v_mfma_f32_16x16x32_bf16 v[16:19], v[162:165], v[212:215], v[16:19]
	v_mfma_f32_16x16x32_bf16 v[8:11], v[154:157], v[240:243], v[8:11]
	v_mfma_f32_16x16x32_bf16 v[4:7], v[162:165], v[240:243], v[4:7]
	s_setprio 0
	s_setprio 1
	v_mfma_f32_16x16x32_bf16 v[60:63], v[176:179], v[192:195], 0
	v_mfma_f32_16x16x32_bf16 v[52:55], v[184:187], v[192:195], 0
	v_mfma_f32_16x16x32_bf16 v[44:47], v[176:179], v[200:203], 0
	v_mfma_f32_16x16x32_bf16 v[36:39], v[184:187], v[200:203], 0
	v_mfma_f32_16x16x32_bf16 v[28:31], v[176:179], v[208:211], 0
	v_mfma_f32_16x16x32_bf16 v[20:23], v[184:187], v[208:211], 0
	v_mfma_f32_16x16x32_bf16 v[12:15], v[176:179], v[216:219], 0
	v_mfma_f32_16x16x32_bf16 v[0:3], v[184:187], v[216:219], 0
	v_mfma_f32_16x16x32_bf16 v[60:63], v[180:183], v[196:199], v[60:63]
	v_mfma_f32_16x16x32_bf16 v[52:55], v[188:191], v[196:199], v[52:55]
	v_mfma_f32_16x16x32_bf16 v[44:47], v[180:183], v[204:207], v[44:47]
	v_mfma_f32_16x16x32_bf16 v[36:39], v[188:191], v[204:207], v[36:39]
	v_mfma_f32_16x16x32_bf16 v[28:31], v[180:183], v[212:215], v[28:31]
	v_mfma_f32_16x16x32_bf16 v[20:23], v[188:191], v[212:215], v[20:23]
	v_mfma_f32_16x16x32_bf16 v[12:15], v[180:183], v[240:243], v[12:15]
	v_mfma_f32_16x16x32_bf16 v[0:3], v[188:191], v[240:243], v[0:3]
	s_setprio 0
	s_barrier
	s_add_i32 s10, 0, 0x18000
	v_add_u32_e32 v150, s10, v151
	s_add_i32 s65, 0, 0x1c000
	ds_read_b128 v[146:149], v150
	ds_read_b128 v[154:157], v150 offset:1024
	ds_read_b128 v[158:161], v150 offset:2048
	ds_read_b128 v[162:165], v150 offset:3072
	v_add_u32_e32 v150, s65, v151
	ds_read_b128 v[176:179], v150
	ds_read_b128 v[180:183], v150 offset:1024
	ds_read_b128 v[184:187], v150 offset:2048
	ds_read_b128 v[188:191], v150 offset:3072
	v_lshl_add_u64 v[166:167], v[166:167], 0, s[94:95]
	s_mov_b32 m0, s53
	v_lshl_add_u64 v[252:253], v[166:167], 0, v[132:133]
	ds_read_b128 v[192:195], v153 offset:32768
	ds_read_b128 v[196:199], v153 offset:33792
	ds_read_b128 v[200:203], v153 offset:34816
	ds_read_b128 v[204:207], v153 offset:35840
	ds_read_b128 v[208:211], v153 offset:36864
	ds_read_b128 v[212:215], v153 offset:37888
	ds_read_b128 v[216:219], v153 offset:38912
	ds_read_b128 v[240:243], v153 offset:39936
	global_load_lds_dwordx4 v[252:253], off
	v_lshl_add_u64 v[166:167], v[166:167], 0, v[130:131]
	s_mov_b32 m0, s54
	s_nop 0
	global_load_lds_dwordx4 v[166:167], off
	s_waitcnt vmcnt(8)
	s_waitcnt lgkmcnt(0)
	s_barrier
; #define PG8_STAGE(bufoff, gbase, voff) do { _Pragma("unroll") for (int _i = 0; _i < 2; ++_i) \
;         __builtin_amdgcn_global_load_lds((const unsigned*)((const char*)(gbase) + (voff)[_i]), (LAS unsigned*)(lds + (bufoff) + ldsw + _i * 8192), 16, 0, 0); } while (0)
; #define PG8_LDA(dst, b, h) do { _Pragma("unroll") for (int m = 0; m < 4; ++m) _Pragma("unroll") for (int k = 0; k < 2; ++k) dst[m][k] = *(const LAS bf16x8*)(lds + PG8_SA(b, h) + aoff + m * 2048 + k * 1024); } while (0)
; #define PG8_MMA(ai, bj, At, Bt) do { __builtin_amdgcn_s_setprio(1); _Pragma("unroll") for (int k = 0; k < 2; ++k) _Pragma("unroll") for (int m = 0; m < 4; ++m) _Pragma("unroll") for (int n = 0; n < 2; ++n) \
;         acc[ai][bj][m][n] = __builtin_amdgcn_mfma_f32_16x16x32_bf16(Bt[n][k], At[m][k], acc[ai][bj][m][n], 0, 0, 0); __builtin_amdgcn_s_setprio(0); } while (0)
; #define PG8_WAIT_V(n) asm volatile("s_waitcnt vmcnt(" #n ")" ::: "memory")
; #define PG8_WAIT_L(n) asm volatile("s_waitcnt lgkmcnt(" #n ")" ::: "memory")
; #define PG8_BAR __builtin_amdgcn_s_barrier()
; #define PG8_SCHED __builtin_amdgcn_sched_barrier(0)
; template <class Epi, bool ALIGN_EPI>
; __device__ __forceinline__ void gemm_phase(LAS unsigned char* lds, const Gemm g, const StaticOrder& S, const Epi& E, const int tid) {
;     ...
;         for (int t = 0; t < nt; t += 2) {
;     ...
;             PG8_WAIT_V(8); PG8_WAIT_L(0); PG8_BAR; PG8_MMA(0, 0, At, B0); PG8_MMA(0, 1, At, B1); PG8_BAR; PG8_SCHED;
;             PG8_LDA(At, 1, 1); PG8_STAGE(PG8_SB(1, 0), b3, voffB); PG8_STAGE(PG8_SB(1, 1), b3 + hB, voffB); PG8_STAGE(PG8_SA(1, 0), a3, voffA);
;             PG8_WAIT_V(8); PG8_WAIT_L(0); PG8_BAR; PG8_MMA(1, 0, At, B0); PG8_MMA(1, 1, At, B1); PG8_BAR; PG8_SCHED;
	s_setprio 1
	s_waitcnt lgkmcnt(0)
	v_mfma_f32_16x16x32_bf16 v[120:123], v[146:149], v[192:195], v[120:123]
	v_mfma_f32_16x16x32_bf16 v[112:115], v[158:161], v[192:195], v[112:115]
	v_mfma_f32_16x16x32_bf16 v[104:107], v[146:149], v[200:203], v[104:107]
	v_mfma_f32_16x16x32_bf16 v[96:99], v[158:161], v[200:203], v[96:99]
	v_mfma_f32_16x16x32_bf16 v[88:91], v[146:149], v[208:211], v[88:91]
	v_mfma_f32_16x16x32_bf16 v[80:83], v[158:161], v[208:211], v[80:83]
	v_mfma_f32_16x16x32_bf16 v[72:75], v[146:149], v[216:219], v[72:75]
	v_mfma_f32_16x16x32_bf16 v[64:67], v[158:161], v[216:219], v[64:67]
	v_mfma_f32_16x16x32_bf16 v[120:123], v[154:157], v[196:199], v[120:123]
	v_mfma_f32_16x16x32_bf16 v[112:115], v[162:165], v[196:199], v[112:115]
	v_mfma_f32_16x16x32_bf16 v[104:107], v[154:157], v[204:207], v[104:107]
	v_mfma_f32_16x16x32_bf16 v[96:99], v[162:165], v[204:207], v[96:99]
	v_mfma_f32_16x16x32_bf16 v[88:91], v[154:157], v[212:215], v[88:91]
	v_mfma_f32_16x16x32_bf16 v[80:83], v[162:165], v[212:215], v[80:83]
	v_mfma_f32_16x16x32_bf16 v[72:75], v[154:157], v[240:243], v[72:75]
	v_mfma_f32_16x16x32_bf16 v[64:67], v[162:165], v[240:243], v[64:67]
	s_setprio 0
	s_setprio 1
	v_mfma_f32_16x16x32_bf16 v[124:127], v[176:179], v[192:195], v[124:127]
	v_mfma_f32_16x16x32_bf16 v[116:119], v[184:187], v[192:195], v[116:119]
	v_mfma_f32_16x16x32_bf16 v[108:111], v[176:179], v[200:203], v[108:111]
	v_mfma_f32_16x16x32_bf16 v[100:103], v[184:187], v[200:203], v[100:103]
	v_mfma_f32_16x16x32_bf16 v[92:95], v[176:179], v[208:211], v[92:95]
	v_mfma_f32_16x16x32_bf16 v[84:87], v[184:187], v[208:211], v[84:87]
	v_mfma_f32_16x16x32_bf16 v[76:79], v[176:179], v[216:219], v[76:79]
	v_mfma_f32_16x16x32_bf16 v[68:71], v[184:187], v[216:219], v[68:71]
	v_mfma_f32_16x16x32_bf16 v[124:127], v[180:183], v[196:199], v[124:127]
	v_mfma_f32_16x16x32_bf16 v[116:119], v[188:191], v[196:199], v[116:119]
	v_mfma_f32_16x16x32_bf16 v[108:111], v[180:183], v[204:207], v[108:111]
	v_mfma_f32_16x16x32_bf16 v[100:103], v[188:191], v[204:207], v[100:103]
	v_mfma_f32_16x16x32_bf16 v[92:95], v[180:183], v[212:215], v[92:95]
	v_mfma_f32_16x16x32_bf16 v[84:87], v[188:191], v[212:215], v[84:87]
	v_mfma_f32_16x16x32_bf16 v[76:79], v[180:183], v[240:243], v[76:79]
	v_mfma_f32_16x16x32_bf16 v[68:71], v[188:191], v[240:243], v[68:71]
	s_setprio 0
	s_barrier
	s_add_i32 s10, s10, s45
	v_lshl_add_u64 v[166:167], v[226:227], 0, s[92:93]
	s_mov_b32 m0, s10
	ds_read_b128 v[192:195], v153 offset:49152
	ds_read_b128 v[196:199], v153 offset:50176
	ds_read_b128 v[200:203], v153 offset:51200
	ds_read_b128 v[204:207], v153 offset:52224
	ds_read_b128 v[208:211], v153 offset:53248
	ds_read_b128 v[212:215], v153 offset:54272
	ds_read_b128 v[216:219], v153 offset:55296
	ds_read_b128 v[240:243], v153 offset:56320
	global_load_lds_dwordx4 v[166:167], off
	v_lshl_add_u64 v[166:167], v[244:245], 0, s[92:93]
	s_add_i32 m0, s10, 0x2000
	s_add_i32 s10, s65, s45
	global_load_lds_dwordx4 v[166:167], off
	v_lshl_add_u64 v[166:167], v[246:247], 0, s[92:93]
	s_mov_b32 m0, s10
	s_nop 0
	global_load_lds_dwordx4 v[166:167], off
	v_lshl_add_u64 v[166:167], v[220:221], 0, s[92:93]
	s_add_i32 m0, s10, 0x2000
	s_nop 0
	global_load_lds_dwordx4 v[166:167], off
	v_lshl_add_u64 v[166:167], v[248:249], 0, s[92:93]
	s_mov_b32 m0, s56
	s_nop 0
	global_load_lds_dwordx4 v[166:167], off
	v_lshl_add_u64 v[166:167], v[250:251], 0, s[92:93]
	s_mov_b32 m0, s57
	s_nop 0
	global_load_lds_dwordx4 v[166:167], off
	s_waitcnt vmcnt(8)
	s_waitcnt lgkmcnt(0)
	s_barrier
	s_setprio 1
	s_waitcnt lgkmcnt(0)
	v_mfma_f32_16x16x32_bf16 v[56:59], v[146:149], v[192:195], v[56:59]
	v_mfma_f32_16x16x32_bf16 v[48:51], v[158:161], v[192:195], v[48:51]
	v_mfma_f32_16x16x32_bf16 v[40:43], v[146:149], v[200:203], v[40:43]
	v_mfma_f32_16x16x32_bf16 v[32:35], v[158:161], v[200:203], v[32:35]
	v_mfma_f32_16x16x32_bf16 v[24:27], v[146:149], v[208:211], v[24:27]
	v_mfma_f32_16x16x32_bf16 v[16:19], v[158:161], v[208:211], v[16:19]
	v_mfma_f32_16x16x32_bf16 v[8:11], v[146:149], v[216:219], v[8:11]
	v_mfma_f32_16x16x32_bf16 v[4:7], v[158:161], v[216:219], v[4:7]
	v_mfma_f32_16x16x32_bf16 v[56:59], v[154:157], v[196:199], v[56:59]
	v_mfma_f32_16x16x32_bf16 v[48:51], v[162:165], v[196:199], v[48:51]
	v_mfma_f32_16x16x32_bf16 v[40:43], v[154:157], v[204:207], v[40:43]
	v_mfma_f32_16x16x32_bf16 v[32:35], v[162:165], v[204:207], v[32:35]
	v_mfma_f32_16x16x32_bf16 v[24:27], v[154:157], v[212:215], v[24:27]
	v_mfma_f32_16x16x32_bf16 v[16:19], v[162:165], v[212:215], v[16:19]
	v_mfma_f32_16x16x32_bf16 v[8:11], v[154:157], v[240:243], v[8:11]
	v_mfma_f32_16x16x32_bf16 v[4:7], v[162:165], v[240:243], v[4:7]
	s_setprio 0
	s_setprio 1
	v_mfma_f32_16x16x32_bf16 v[60:63], v[176:179], v[192:195], v[60:63]
	v_mfma_f32_16x16x32_bf16 v[52:55], v[184:187], v[192:195], v[52:55]
	v_mfma_f32_16x16x32_bf16 v[44:47], v[176:179], v[200:203], v[44:47]
	v_mfma_f32_16x16x32_bf16 v[36:39], v[184:187], v[200:203], v[36:39]
	v_mfma_f32_16x16x32_bf16 v[28:31], v[176:179], v[208:211], v[28:31]
	v_mfma_f32_16x16x32_bf16 v[20:23], v[184:187], v[208:211], v[20:23]
	v_mfma_f32_16x16x32_bf16 v[12:15], v[176:179], v[216:219], v[12:15]
	v_mfma_f32_16x16x32_bf16 v[0:3], v[184:187], v[216:219], v[0:3]
	v_mfma_f32_16x16x32_bf16 v[60:63], v[180:183], v[196:199], v[60:63]
	v_mfma_f32_16x16x32_bf16 v[52:55], v[188:191], v[196:199], v[52:55]
	v_mfma_f32_16x16x32_bf16 v[44:47], v[180:183], v[204:207], v[44:47]
	v_mfma_f32_16x16x32_bf16 v[36:39], v[188:191], v[204:207], v[36:39]
	v_mfma_f32_16x16x32_bf16 v[28:31], v[180:183], v[212:215], v[28:31]
	v_mfma_f32_16x16x32_bf16 v[20:23], v[188:191], v[212:215], v[20:23]
	v_mfma_f32_16x16x32_bf16 v[12:15], v[180:183], v[240:243], v[12:15]
	v_mfma_f32_16x16x32_bf16 v[0:3], v[188:191], v[240:243], v[0:3]
	s_setprio 0
	s_barrier
	v_lshl_add_u64 v[142:143], v[142:143], 0, s[80:81]
	v_lshl_add_u64 v[144:145], v[144:145], 0, s[80:81]
	s_mov_b32 s10, s11
	s_cmp_eq_u32 s10, s58
	s_cbranch_scc1 .Lgu_last
	s_branch .LBB0_308

; #define PG8_STAGE(bufoff, gbase, voff) do { _Pragma("unroll") for (int _i = 0; _i < 2; ++_i) \
;         __builtin_amdgcn_global_load_lds((const unsigned*)((const char*)(gbase) + (voff)[_i]), (LAS unsigned*)(lds + (bufoff) + ldsw + _i * 8192), 16, 0, 0); } while (0)
; #define PG8_LDA(dst, b, h) do { _Pragma("unroll") for (int m = 0; m < 4; ++m) _Pragma("unroll") for (int k = 0; k < 2; ++k) dst[m][k] = *(const LAS bf16x8*)(lds + PG8_SA(b, h) + aoff + m * 2048 + k * 1024); } while (0)
; #define PG8_LDB(dst, b, h) do { _Pragma("unroll") for (int n = 0; n < 2; ++n) _Pragma("unroll") for (int k = 0; k < 2; ++k) dst[n][k] = *(const LAS bf16x8*)(lds + PG8_SB(b, h) + boff + n * 2048 + k * 1024); } while (0)
; #define PG8_MMA(ai, bj, At, Bt) do { __builtin_amdgcn_s_setprio(1); _Pragma("unroll") for (int k = 0; k < 2; ++k) _Pragma("unroll") for (int m = 0; m < 4; ++m) _Pragma("unroll") for (int n = 0; n < 2; ++n) \
;         acc[ai][bj][m][n] = __builtin_amdgcn_mfma_f32_16x16x32_bf16(Bt[n][k], At[m][k], acc[ai][bj][m][n], 0, 0, 0); __builtin_amdgcn_s_setprio(0); } while (0)
; #define PG8_WAIT_V(n) asm volatile("s_waitcnt vmcnt(" #n ")" ::: "memory")
; #define PG8_WAIT_L(n) asm volatile("s_waitcnt lgkmcnt(" #n ")" ::: "memory")
; #define PG8_BAR __builtin_amdgcn_s_barrier()
; #define PG8_SCHED __builtin_amdgcn_sched_barrier(0)
; template <class Epi, bool ALIGN_EPI>
; __device__ __forceinline__ void gemm_phase(LAS unsigned char* lds, const Gemm g, const StaticOrder& S, const Epi& E, const int tid) {
;     ...
;             const bool last = (t == nt - 2);
;             const char* a1 = cA + (size_t)(t + 1) * kstep;
;             const char* a2 = last ? nA : cA + (size_t)(t + 2) * kstep; const char* b2 = last ? nB : cB + (size_t)(t + 2) * kstep;
;             const char* a3 = a2 + kstep; const char* b3 = b2 + kstep;
;             PG8_LDB(B0, 0, 0); PG8_LDB(B1, 0, 1); PG8_SCHED; PG8_LDA(At, 0, 0); PG8_STAGE(PG8_SA(1, 1), a1 + hA, voffA);
;             PG8_WAIT_V(8); PG8_WAIT_L(0); PG8_BAR; PG8_MMA(0, 0, At, B0); PG8_MMA(0, 1, At, B1); PG8_BAR; PG8_SCHED;
;             PG8_LDA(At, 0, 1); PG8_STAGE(PG8_SB(0, 0), b2, voffB); PG8_STAGE(PG8_SB(0, 1), b2 + hB, voffB); PG8_STAGE(PG8_SA(0, 0), a2, voffA);
.Lgu_last:
	s_add_i32 s11, s10, 2
	s_cmp_eq_u32 s58, s10
	v_lshl_add_u64 v[146:147], v[142:143], 0, s[92:93]
	s_cselect_b64 vcc, -1, 0
	v_add_u32_e32 v150, s33, v151
	s_add_i32 s10, 0, 0x14000
	v_cndmask_b32_e32 v167, v147, v139, vcc
	v_cndmask_b32_e32 v166, v146, v138, vcc
	ds_read_b128 v[146:149], v150
	ds_read_b128 v[154:157], v150 offset:1024
	ds_read_b128 v[158:161], v150 offset:2048
	ds_read_b128 v[162:165], v150 offset:3072
	v_add_u32_e32 v150, s10, v151
	ds_read_b128 v[176:179], v150
	ds_read_b128 v[180:183], v150 offset:1024
	ds_read_b128 v[184:187], v150 offset:2048
	ds_read_b128 v[188:191], v150 offset:3072
	v_cndmask_b32_e32 v221, v145, v141, vcc
	v_cndmask_b32_e32 v220, v144, v140, vcc
	v_lshl_add_u64 v[226:227], v[142:143], 0, v[134:135]
	s_add_i32 m0, s51, 0xc000
	ds_read_b128 v[192:195], v153
	ds_read_b128 v[196:199], v153 offset:1024
	ds_read_b128 v[200:203], v153 offset:2048
	ds_read_b128 v[204:207], v153 offset:3072
	ds_read_b128 v[208:211], v153 offset:4096
	ds_read_b128 v[212:215], v153 offset:5120
	ds_read_b128 v[216:219], v153 offset:6144
	ds_read_b128 v[240:243], v153 offset:7168
	global_load_lds_dwordx4 v[226:227], off
	v_lshl_add_u64 v[226:227], v[142:143], 0, v[136:137]
	s_add_i32 m0, s51, 0xe000
	s_nop 0
	global_load_lds_dwordx4 v[226:227], off
	s_waitcnt vmcnt(8)
	s_waitcnt lgkmcnt(0)
	s_barrier
	s_setprio 1
	s_waitcnt lgkmcnt(0)
	v_mfma_f32_16x16x32_bf16 v[120:123], v[146:149], v[192:195], v[120:123]
	v_mfma_f32_16x16x32_bf16 v[112:115], v[158:161], v[192:195], v[112:115]
	v_mfma_f32_16x16x32_bf16 v[104:107], v[146:149], v[200:203], v[104:107]
	v_mfma_f32_16x16x32_bf16 v[96:99], v[158:161], v[200:203], v[96:99]
	v_mfma_f32_16x16x32_bf16 v[88:91], v[146:149], v[208:211], v[88:91]
	v_mfma_f32_16x16x32_bf16 v[80:83], v[158:161], v[208:211], v[80:83]
	v_mfma_f32_16x16x32_bf16 v[72:75], v[146:149], v[216:219], v[72:75]
	v_mfma_f32_16x16x32_bf16 v[64:67], v[158:161], v[216:219], v[64:67]
	v_mfma_f32_16x16x32_bf16 v[120:123], v[154:157], v[196:199], v[120:123]
	v_mfma_f32_16x16x32_bf16 v[112:115], v[162:165], v[196:199], v[112:115]
	v_mfma_f32_16x16x32_bf16 v[104:107], v[154:157], v[204:207], v[104:107]
	v_mfma_f32_16x16x32_bf16 v[96:99], v[162:165], v[204:207], v[96:99]
	v_mfma_f32_16x16x32_bf16 v[88:91], v[154:157], v[212:215], v[88:91]
	v_mfma_f32_16x16x32_bf16 v[80:83], v[162:165], v[212:215], v[80:83]
	v_mfma_f32_16x16x32_bf16 v[72:75], v[154:157], v[240:243], v[72:75]
	v_mfma_f32_16x16x32_bf16 v[64:67], v[162:165], v[240:243], v[64:67]
	s_setprio 0
	s_setprio 1
	v_mfma_f32_16x16x32_bf16 v[124:127], v[176:179], v[192:195], v[124:127]
	v_mfma_f32_16x16x32_bf16 v[116:119], v[184:187], v[192:195], v[116:119]
	v_mfma_f32_16x16x32_bf16 v[108:111], v[176:179], v[200:203], v[108:111]
	v_mfma_f32_16x16x32_bf16 v[100:103], v[184:187], v[200:203], v[100:103]
	v_mfma_f32_16x16x32_bf16 v[92:95], v[176:179], v[208:211], v[92:95]
	v_mfma_f32_16x16x32_bf16 v[84:87], v[184:187], v[208:211], v[84:87]
	v_mfma_f32_16x16x32_bf16 v[76:79], v[176:179], v[216:219], v[76:79]
	v_mfma_f32_16x16x32_bf16 v[68:71], v[184:187], v[216:219], v[68:71]
	v_mfma_f32_16x16x32_bf16 v[124:127], v[180:183], v[196:199], v[124:127]
	v_mfma_f32_16x16x32_bf16 v[116:119], v[188:191], v[196:199], v[116:119]
	v_mfma_f32_16x16x32_bf16 v[108:111], v[180:183], v[204:207], v[108:111]
	v_mfma_f32_16x16x32_bf16 v[100:103], v[188:191], v[204:207], v[100:103]
	v_mfma_f32_16x16x32_bf16 v[92:95], v[180:183], v[212:215], v[92:95]
	v_mfma_f32_16x16x32_bf16 v[84:87], v[188:191], v[212:215], v[84:87]
	v_mfma_f32_16x16x32_bf16 v[76:79], v[180:183], v[240:243], v[76:79]
	v_mfma_f32_16x16x32_bf16 v[68:71], v[188:191], v[240:243], v[68:71]
	s_setprio 0
	s_barrier
	s_add_i32 s65, s33, s45
	v_lshl_add_u64 v[226:227], v[220:221], 0, v[168:169]
	s_mov_b32 m0, s65
	ds_read_b128 v[192:195], v153 offset:16384
	ds_read_b128 v[196:199], v153 offset:17408
	ds_read_b128 v[200:203], v153 offset:18432
	ds_read_b128 v[204:207], v153 offset:19456
	ds_read_b128 v[208:211], v153 offset:20480
	ds_read_b128 v[212:215], v153 offset:21504
	ds_read_b128 v[216:219], v153 offset:22528
	ds_read_b128 v[240:243], v153 offset:23552
	global_load_lds_dwordx4 v[226:227], off
	v_lshl_add_u64 v[244:245], v[220:221], 0, v[128:129]
	s_add_i32 m0, s65, 0x2000
	v_lshl_add_u64 v[220:221], v[220:221], 0, s[12:13]
	s_add_i32 s10, s10, s45
	global_load_lds_dwordx4 v[244:245], off
	v_lshl_add_u64 v[246:247], v[220:221], 0, v[168:169]
	s_mov_b32 m0, s10
	v_lshl_add_u64 v[220:221], v[220:221], 0, v[128:129]
	global_load_lds_dwordx4 v[246:247], off
	s_add_i32 m0, s10, 0x2000
	v_lshl_add_u64 v[248:249], v[166:167], 0, v[132:133]
	global_load_lds_dwordx4 v[220:221], off
	s_mov_b32 m0, s51
	v_lshl_add_u64 v[250:251], v[166:167], 0, v[130:131]
	global_load_lds_dwordx4 v[248:249], off
	s_mov_b32 m0, s52
	s_nop 0
	global_load_lds_dwordx4 v[250:251], off
	s_waitcnt vmcnt(8)
	s_waitcnt lgkmcnt(0)
	s_barrier
; #define PG8_STAGE(bufoff, gbase, voff) do { _Pragma("unroll") for (int _i = 0; _i < 2; ++_i) \
;         __builtin_amdgcn_global_load_lds((const unsigned*)((const char*)(gbase) + (voff)[_i]), (LAS unsigned*)(lds + (bufoff) + ldsw + _i * 8192), 16, 0, 0); } while (0)
; #define PG8_LDA(dst, b, h) do { _Pragma("unroll") for (int m = 0; m < 4; ++m) _Pragma("unroll") for (int k = 0; k < 2; ++k) dst[m][k] = *(const LAS bf16x8*)(lds + PG8_SA(b, h) + aoff + m * 2048 + k * 1024); } while (0)
; #define PG8_LDB(dst, b, h) do { _Pragma("unroll") for (int n = 0; n < 2; ++n) _Pragma("unroll") for (int k = 0; k < 2; ++k) dst[n][k] = *(const LAS bf16x8*)(lds + PG8_SB(b, h) + boff + n * 2048 + k * 1024); } while (0)
; #define PG8_MMA(ai, bj, At, Bt) do { __builtin_amdgcn_s_setprio(1); _Pragma("unroll") for (int k = 0; k < 2; ++k) _Pragma("unroll") for (int m = 0; m < 4; ++m) _Pragma("unroll") for (int n = 0; n < 2; ++n) \
;         acc[ai][bj][m][n] = __builtin_amdgcn_mfma_f32_16x16x32_bf16(Bt[n][k], At[m][k], acc[ai][bj][m][n], 0, 0, 0); __builtin_amdgcn_s_setprio(0); } while (0)
; #define PG8_WAIT_V(n) asm volatile("s_waitcnt vmcnt(" #n ")" ::: "memory")
; #define PG8_WAIT_L(n) asm volatile("s_waitcnt lgkmcnt(" #n ")" ::: "memory")
; #define PG8_BAR __builtin_amdgcn_s_barrier()
; #define PG8_SCHED __builtin_amdgcn_sched_barrier(0)
; template <class Epi, bool ALIGN_EPI>
; __device__ __forceinline__ void gemm_phase(LAS unsigned char* lds, const Gemm g, const StaticOrder& S, const Epi& E, const int tid) {
;     ...
;             PG8_WAIT_V(8); PG8_WAIT_L(0); PG8_BAR; PG8_MMA(1, 0, At, B0); PG8_MMA(1, 1, At, B1); PG8_BAR; PG8_SCHED;
;             PG8_LDB(B0, 1, 0); PG8_LDB(B1, 1, 1); PG8_SCHED; PG8_LDA(At, 1, 0); PG8_STAGE(PG8_SA(0, 1), a2 + hA, voffA);
;             PG8_WAIT_V(8); PG8_WAIT_L(0); PG8_BAR; PG8_MMA(0, 0, At, B0); PG8_MMA(0, 1, At, B1); PG8_BAR; PG8_SCHED;
	s_setprio 1
	s_waitcnt lgkmcnt(0)
	v_mfma_f32_16x16x32_bf16 v[56:59], v[146:149], v[192:195], v[56:59]
	v_mfma_f32_16x16x32_bf16 v[48:51], v[158:161], v[192:195], v[48:51]
	v_mfma_f32_16x16x32_bf16 v[40:43], v[146:149], v[200:203], v[40:43]
	v_mfma_f32_16x16x32_bf16 v[32:35], v[158:161], v[200:203], v[32:35]
	v_mfma_f32_16x16x32_bf16 v[24:27], v[146:149], v[208:211], v[24:27]
	v_mfma_f32_16x16x32_bf16 v[16:19], v[158:161], v[208:211], v[16:19]
	v_mfma_f32_16x16x32_bf16 v[8:11], v[146:149], v[216:219], v[8:11]
	v_mfma_f32_16x16x32_bf16 v[4:7], v[158:161], v[216:219], v[4:7]
	v_mfma_f32_16x16x32_bf16 v[56:59], v[154:157], v[196:199], v[56:59]
	v_mfma_f32_16x16x32_bf16 v[48:51], v[162:165], v[196:199], v[48:51]
	v_mfma_f32_16x16x32_bf16 v[40:43], v[154:157], v[204:207], v[40:43]
	v_mfma_f32_16x16x32_bf16 v[32:35], v[162:165], v[204:207], v[32:35]
	v_mfma_f32_16x16x32_bf16 v[24:27], v[154:157], v[212:215], v[24:27]
	v_mfma_f32_16x16x32_bf16 v[16:19], v[162:165], v[212:215], v[16:19]
	v_mfma_f32_16x16x32_bf16 v[8:11], v[154:157], v[240:243], v[8:11]
	v_mfma_f32_16x16x32_bf16 v[4:7], v[162:165], v[240:243], v[4:7]
	s_setprio 0
	s_setprio 1
	v_mfma_f32_16x16x32_bf16 v[60:63], v[176:179], v[192:195], v[60:63]
	v_mfma_f32_16x16x32_bf16 v[52:55], v[184:187], v[192:195], v[52:55]
	v_mfma_f32_16x16x32_bf16 v[44:47], v[176:179], v[200:203], v[44:47]
	v_mfma_f32_16x16x32_bf16 v[36:39], v[184:187], v[200:203], v[36:39]
	v_mfma_f32_16x16x32_bf16 v[28:31], v[176:179], v[208:211], v[28:31]
	v_mfma_f32_16x16x32_bf16 v[20:23], v[184:187], v[208:211], v[20:23]
	v_mfma_f32_16x16x32_bf16 v[12:15], v[176:179], v[216:219], v[12:15]
	v_mfma_f32_16x16x32_bf16 v[0:3], v[184:187], v[216:219], v[0:3]
	v_mfma_f32_16x16x32_bf16 v[60:63], v[180:183], v[196:199], v[60:63]
	v_mfma_f32_16x16x32_bf16 v[52:55], v[188:191], v[196:199], v[52:55]
	v_mfma_f32_16x16x32_bf16 v[44:47], v[180:183], v[204:207], v[44:47]
	v_mfma_f32_16x16x32_bf16 v[36:39], v[188:191], v[204:207], v[36:39]
	v_mfma_f32_16x16x32_bf16 v[28:31], v[180:183], v[212:215], v[28:31]
	v_mfma_f32_16x16x32_bf16 v[20:23], v[188:191], v[212:215], v[20:23]
	v_mfma_f32_16x16x32_bf16 v[12:15], v[180:183], v[240:243], v[12:15]
	v_mfma_f32_16x16x32_bf16 v[0:3], v[188:191], v[240:243], v[0:3]
	s_setprio 0
	s_barrier
	s_add_i32 s10, 0, 0x18000
	v_add_u32_e32 v150, s10, v151
	s_add_i32 s65, 0, 0x1c000
	ds_read_b128 v[146:149], v150
	ds_read_b128 v[154:157], v150 offset:1024
	ds_read_b128 v[158:161], v150 offset:2048
	ds_read_b128 v[162:165], v150 offset:3072
	v_add_u32_e32 v150, s65, v151
	ds_read_b128 v[176:179], v150
	ds_read_b128 v[180:183], v150 offset:1024
	ds_read_b128 v[184:187], v150 offset:2048
	ds_read_b128 v[188:191], v150 offset:3072
	v_lshl_add_u64 v[166:167], v[166:167], 0, s[94:95]
	s_mov_b32 m0, s53
	v_lshl_add_u64 v[252:253], v[166:167], 0, v[132:133]
	ds_read_b128 v[192:195], v153 offset:32768
	ds_read_b128 v[196:199], v153 offset:33792
	ds_read_b128 v[200:203], v153 offset:34816
	ds_read_b128 v[204:207], v153 offset:35840
	ds_read_b128 v[208:211], v153 offset:36864
	ds_read_b128 v[212:215], v153 offset:37888
	ds_read_b128 v[216:219], v153 offset:38912
	ds_read_b128 v[240:243], v153 offset:39936
	global_load_lds_dwordx4 v[252:253], off
	v_lshl_add_u64 v[166:167], v[166:167], 0, v[130:131]
	s_mov_b32 m0, s54
	s_nop 0
	global_load_lds_dwordx4 v[166:167], off
	s_waitcnt vmcnt(8)
	s_waitcnt lgkmcnt(0)
	s_barrier
	s_setprio 1
	s_waitcnt lgkmcnt(0)
	v_mfma_f32_16x16x32_bf16 v[120:123], v[146:149], v[192:195], v[120:123]
	v_mfma_f32_16x16x32_bf16 v[112:115], v[158:161], v[192:195], v[112:115]
	v_mfma_f32_16x16x32_bf16 v[104:107], v[146:149], v[200:203], v[104:107]
	v_mfma_f32_16x16x32_bf16 v[96:99], v[158:161], v[200:203], v[96:99]
	v_mfma_f32_16x16x32_bf16 v[88:91], v[146:149], v[208:211], v[88:91]
	v_mfma_f32_16x16x32_bf16 v[80:83], v[158:161], v[208:211], v[80:83]
	v_mfma_f32_16x16x32_bf16 v[72:75], v[146:149], v[216:219], v[72:75]
	v_mfma_f32_16x16x32_bf16 v[64:67], v[158:161], v[216:219], v[64:67]
	v_mfma_f32_16x16x32_bf16 v[120:123], v[154:157], v[196:199], v[120:123]
	v_mfma_f32_16x16x32_bf16 v[112:115], v[162:165], v[196:199], v[112:115]
	v_mfma_f32_16x16x32_bf16 v[104:107], v[154:157], v[204:207], v[104:107]
	v_mfma_f32_16x16x32_bf16 v[96:99], v[162:165], v[204:207], v[96:99]
	v_mfma_f32_16x16x32_bf16 v[88:91], v[154:157], v[212:215], v[88:91]
	v_mfma_f32_16x16x32_bf16 v[80:83], v[162:165], v[212:215], v[80:83]
	v_mfma_f32_16x16x32_bf16 v[72:75], v[154:157], v[240:243], v[72:75]
	v_mfma_f32_16x16x32_bf16 v[64:67], v[162:165], v[240:243], v[64:67]
	s_setprio 0
	s_setprio 1
	v_mfma_f32_16x16x32_bf16 v[124:127], v[176:179], v[192:195], v[124:127]
	v_mfma_f32_16x16x32_bf16 v[116:119], v[184:187], v[192:195], v[116:119]
	v_mfma_f32_16x16x32_bf16 v[108:111], v[176:179], v[200:203], v[108:111]
	v_mfma_f32_16x16x32_bf16 v[100:103], v[184:187], v[200:203], v[100:103]
	v_mfma_f32_16x16x32_bf16 v[92:95], v[176:179], v[208:211], v[92:95]
	v_mfma_f32_16x16x32_bf16 v[84:87], v[184:187], v[208:211], v[84:87]
	v_mfma_f32_16x16x32_bf16 v[76:79], v[176:179], v[216:219], v[76:79]
	v_mfma_f32_16x16x32_bf16 v[68:71], v[184:187], v[216:219], v[68:71]
	v_mfma_f32_16x16x32_bf16 v[124:127], v[180:183], v[196:199], v[124:127]
	v_mfma_f32_16x16x32_bf16 v[116:119], v[188:191], v[196:199], v[116:119]
	v_mfma_f32_16x16x32_bf16 v[108:111], v[180:183], v[204:207], v[108:111]
	v_mfma_f32_16x16x32_bf16 v[100:103], v[188:191], v[204:207], v[100:103]
	v_mfma_f32_16x16x32_bf16 v[92:95], v[180:183], v[212:215], v[92:95]
	v_mfma_f32_16x16x32_bf16 v[84:87], v[188:191], v[212:215], v[84:87]
	v_mfma_f32_16x16x32_bf16 v[76:79], v[180:183], v[240:243], v[76:79]
	v_mfma_f32_16x16x32_bf16 v[68:71], v[188:191], v[240:243], v[68:71]
	s_setprio 0
	s_barrier
; __device__ __forceinline__ unsigned cvt_pk_bf16(float lo, float hi) { unsigned r; asm volatile("v_cvt_pk_bf16_f32 %0, %1, %2" : "=v"(r) : "v"(lo), "v"(hi)); return r; }
; __device__ __forceinline__ float siluf_(float x) { return x * sigmoidf_(x); }
; #define PG8_STAGE(bufoff, gbase, voff) do { _Pragma("unroll") for (int _i = 0; _i < 2; ++_i) \
;         __builtin_amdgcn_global_load_lds((const unsigned*)((const char*)(gbase) + (voff)[_i]), (LAS unsigned*)(lds + (bufoff) + ldsw + _i * 8192), 16, 0, 0); } while (0)
; #define PG8_LDA(dst, b, h) do { _Pragma("unroll") for (int m = 0; m < 4; ++m) _Pragma("unroll") for (int k = 0; k < 2; ++k) dst[m][k] = *(const LAS bf16x8*)(lds + PG8_SA(b, h) + aoff + m * 2048 + k * 1024); } while (0)
; #define PG8_WAIT_V(n) asm volatile("s_waitcnt vmcnt(" #n ")" ::: "memory")
; #define PG8_WAIT_L(n) asm volatile("s_waitcnt lgkmcnt(" #n ")" ::: "memory")
; #define PG8_BAR __builtin_amdgcn_s_barrier()
; #define PG8_SCHED __builtin_amdgcn_sched_barrier(0)
;     __device__ __forceinline__ void operator()(const f32x4 (&acc)[2][2][4][2], const Unit& u, int wr, int wc, int fr, int fq) const {
;         const int row0 = u.pm * BM + wr * 64 + fr, col0 = u.pn * HALF + wc * 32 + 8 * fq;
;         float rsv[2][4]; load_rstd(rsv, ssq, row0);
; #pragma unroll
;         for (int ai = 0; ai < 2; ++ai)
; #pragma unroll
;             for (int m = 0; m < 4; ++m) { const int row = row0 + ai * HALF + m * 16; bf16_t* rowp = O + (size_t)row * ldc + col0; const float rs = rsv[ai][m];
;                 f32x4 v0, v1;
; #pragma unroll
;                 for (int j = 0; j < 4; ++j) { v0[j] = siluf_(acc[ai][0][m][0][j] * rs) * (acc[ai][1][m][0][j] * rs); v1[j] = siluf_(acc[ai][0][m][1][j] * rs) * (acc[ai][1][m][1][j] * rs); }
;                 u32x4 w; w.x = cvt_pk_bf16(v0[0], v0[1]); w.y = cvt_pk_bf16(v0[2], v0[3]); w.z = cvt_pk_bf16(v1[0], v1[1]); w.w = cvt_pk_bf16(v1[2], v1[3]);
;                 *(u32x4*)rowp = w; }
; template <class Epi, bool ALIGN_EPI>
; __device__ __forceinline__ void gemm_phase(LAS unsigned char* lds, const Gemm g, const StaticOrder& S, const Epi& E, const int tid) {
;     ...
;             PG8_LDA(At, 1, 1); PG8_STAGE(PG8_SB(1, 0), b3, voffB); PG8_STAGE(PG8_SB(1, 1), b3 + hB, voffB); PG8_STAGE(PG8_SA(1, 0), a3, voffA);
;             PG8_WAIT_V(8); PG8_WAIT_L(0); PG8_BAR; PG8_MMA(1, 0, At, B0); PG8_MMA(1, 1, At, B1); PG8_BAR; PG8_SCHED;
	s_add_i32 s10, s10, s45
	v_lshl_add_u64 v[166:167], v[226:227], 0, s[92:93]
	s_mov_b32 m0, s10
	ds_read_b128 v[192:195], v153 offset:49152
	ds_read_b128 v[196:199], v153 offset:50176
	ds_read_b128 v[200:203], v153 offset:51200
	ds_read_b128 v[204:207], v153 offset:52224
	ds_read_b128 v[208:211], v153 offset:53248
	ds_read_b128 v[212:215], v153 offset:54272
	ds_read_b128 v[216:219], v153 offset:55296
	ds_read_b128 v[240:243], v153 offset:56320
	global_load_lds_dwordx4 v[166:167], off
	v_lshl_add_u64 v[166:167], v[244:245], 0, s[92:93]
	s_add_i32 m0, s10, 0x2000
	s_add_i32 s10, s65, s45
	global_load_lds_dwordx4 v[166:167], off
	v_lshl_add_u64 v[166:167], v[246:247], 0, s[92:93]
	s_mov_b32 m0, s10
	s_nop 0
	global_load_lds_dwordx4 v[166:167], off
	v_lshl_add_u64 v[166:167], v[220:221], 0, s[92:93]
	s_add_i32 m0, s10, 0x2000
	s_nop 0
	global_load_lds_dwordx4 v[166:167], off
	v_lshl_add_u64 v[166:167], v[248:249], 0, s[92:93]
	s_mov_b32 m0, s56
	s_nop 0
	global_load_lds_dwordx4 v[166:167], off
	v_lshl_add_u64 v[166:167], v[250:251], 0, s[92:93]
	s_mov_b32 m0, s57
	s_nop 0
	global_load_lds_dwordx4 v[166:167], off
	s_waitcnt vmcnt(8)
	s_waitcnt lgkmcnt(0)
	s_barrier
	s_setprio 1
	s_waitcnt lgkmcnt(0)
	v_mfma_f32_16x16x32_bf16 v[56:59], v[146:149], v[192:195], v[56:59]
	v_lshrrev_b32_e32 v171, 8, v170
	v_and_b32_e32 v234, 15, v170
	v_lshl_add_u32 v171, v171, 6, v234
	s_lshl_b32 s98, s64, 8
	v_add_u32_e32 v171, s98, v171
	v_mul_lo_u32 v171, v171, s28
	v_bfe_u32 v234, v170, 6, 2
	v_bfe_u32 v224, v170, 4, 2
	v_lshlrev_b32_e32 v234, 5, v234
	v_lshl_or_b32 v234, v224, 3, v234
	v_mfma_f32_16x16x32_bf16 v[48:51], v[158:161], v[192:195], v[48:51]
	s_lshl_b32 s98, s63, 7
	v_add_u32_e32 v234, s98, v234
	v_add_lshl_u32 v232, v171, v234, 1
	v_mov_b32_e32 v233, 0
	v_lshl_add_u64 v[232:233], v[232:233], 0, s[30:31]
	s_lshl_b32 s98, s28, 5
	s_mov_b32 s99, 0
	s_mov_b32 s100, 0xbfb8aa3b
	s_mov_b32 s101, 0xbfb8aa3b
	v_mul_f32_e32 v120, v172, v120
	v_mfma_f32_16x16x32_bf16 v[40:43], v[146:149], v[200:203], v[40:43]
	v_mul_f32_e32 v121, v172, v121
	v_mul_f32_e32 v122, v172, v122
	v_mul_f32_e32 v123, v172, v123
	v_mul_f32_e32 v124, v172, v124
	v_mul_f32_e32 v125, v172, v125
	v_mul_f32_e32 v126, v172, v126
	v_mul_f32_e32 v127, v172, v127
	v_mul_f32_e32 v224, s100, v120
	v_mul_f32_e32 v225, s101, v121
	v_mul_f32_e32 v228, s100, v122
	v_mfma_f32_16x16x32_bf16 v[32:35], v[158:161], v[200:203], v[32:35]
	v_mul_f32_e32 v229, s101, v123
	v_exp_f32_e32 v224, v224
	v_exp_f32_e32 v225, v225
	v_exp_f32_e32 v228, v228
	v_exp_f32_e32 v229, v229
	v_add_f32_e32 v224, 1.0, v224
	v_add_f32_e32 v225, 1.0, v225
	v_add_f32_e32 v228, 1.0, v228
	v_add_f32_e32 v229, 1.0, v229
	v_rcp_f32_e32 v224, v224
	v_mfma_f32_16x16x32_bf16 v[24:27], v[146:149], v[208:211], v[24:27]
	v_rcp_f32_e32 v225, v225
	v_rcp_f32_e32 v228, v228
	v_rcp_f32_e32 v229, v229
	v_nop
	v_mul_f32_e32 v120, v224, v120
	v_mul_f32_e32 v121, v225, v121
	v_mul_f32_e32 v122, v228, v122
	v_mul_f32_e32 v123, v229, v123
	v_mul_f32_e32 v120, v124, v120
	v_mul_f32_e32 v121, v125, v121
	v_mfma_f32_16x16x32_bf16 v[16:19], v[158:161], v[208:211], v[16:19]
	v_mul_f32_e32 v122, v126, v122
	v_mul_f32_e32 v123, v127, v123
	v_mul_f32_e32 v112, v172, v112
	v_mul_f32_e32 v113, v172, v113
	v_mul_f32_e32 v114, v172, v114
	v_mul_f32_e32 v115, v172, v115
	v_mul_f32_e32 v116, v172, v116
	v_mul_f32_e32 v117, v172, v117
	v_mul_f32_e32 v118, v172, v118
	v_mul_f32_e32 v119, v172, v119
	v_mfma_f32_16x16x32_bf16 v[8:11], v[146:149], v[216:219], v[8:11]
	v_mul_f32_e32 v224, s100, v112
	v_mul_f32_e32 v225, s101, v113
	v_mul_f32_e32 v228, s100, v114
	v_mul_f32_e32 v229, s101, v115
	v_exp_f32_e32 v224, v224
	v_exp_f32_e32 v225, v225
	v_exp_f32_e32 v228, v228
	v_exp_f32_e32 v229, v229
	v_add_f32_e32 v224, 1.0, v224
	v_add_f32_e32 v225, 1.0, v225
	v_mfma_f32_16x16x32_bf16 v[4:7], v[158:161], v[216:219], v[4:7]
	v_add_f32_e32 v228, 1.0, v228
	v_add_f32_e32 v229, 1.0, v229
	v_rcp_f32_e32 v224, v224
	v_rcp_f32_e32 v225, v225
	v_rcp_f32_e32 v228, v228
	v_rcp_f32_e32 v229, v229
	v_nop
	v_mul_f32_e32 v112, v224, v112
	v_mul_f32_e32 v113, v225, v113
	v_mul_f32_e32 v114, v228, v114
	v_mfma_f32_16x16x32_bf16 v[56:59], v[154:157], v[196:199], v[56:59]
	v_mul_f32_e32 v115, v229, v115
	v_mul_f32_e32 v112, v116, v112
	v_mul_f32_e32 v113, v117, v113
	v_mul_f32_e32 v114, v118, v114
	v_mul_f32_e32 v115, v119, v115
	v_cvt_pk_bf16_f32 v120, v120, v121
	v_cvt_pk_bf16_f32 v121, v122, v123
	v_cvt_pk_bf16_f32 v122, v112, v113
	v_cvt_pk_bf16_f32 v123, v114, v115
	global_store_dwordx4 v[232:233], v[120:123], off
	v_mfma_f32_16x16x32_bf16 v[48:51], v[162:165], v[196:199], v[48:51]
	v_lshl_add_u64 v[232:233], v[232:233], 0, s[98:99]
	v_mul_f32_e32 v104, v173, v104
	v_mul_f32_e32 v105, v173, v105
	v_mul_f32_e32 v106, v173, v106
	v_mul_f32_e32 v107, v173, v107
	v_mul_f32_e32 v108, v173, v108
	v_mul_f32_e32 v109, v173, v109
	v_mul_f32_e32 v110, v173, v110
	v_mul_f32_e32 v111, v173, v111
	v_mul_f32_e32 v224, s100, v104
	v_mfma_f32_16x16x32_bf16 v[40:43], v[154:157], v[204:207], v[40:43]
	v_mul_f32_e32 v225, s101, v105
	v_mul_f32_e32 v228, s100, v106
	v_mul_f32_e32 v229, s101, v107
	v_exp_f32_e32 v224, v224
	v_exp_f32_e32 v225, v225
	v_exp_f32_e32 v228, v228
	v_exp_f32_e32 v229, v229
	v_add_f32_e32 v224, 1.0, v224
	v_add_f32_e32 v225, 1.0, v225
	v_add_f32_e32 v228, 1.0, v228
	v_mfma_f32_16x16x32_bf16 v[32:35], v[162:165], v[204:207], v[32:35]
	v_add_f32_e32 v229, 1.0, v229
	v_rcp_f32_e32 v224, v224
	v_rcp_f32_e32 v225, v225
	v_rcp_f32_e32 v228, v228
	v_rcp_f32_e32 v229, v229
	v_nop
	v_mul_f32_e32 v104, v224, v104
	v_mul_f32_e32 v105, v225, v105
	v_mul_f32_e32 v106, v228, v106
; __device__ __forceinline__ unsigned cvt_pk_bf16(float lo, float hi) { unsigned r; asm volatile("v_cvt_pk_bf16_f32 %0, %1, %2" : "=v"(r) : "v"(lo), "v"(hi)); return r; }
; __device__ __forceinline__ float siluf_(float x) { return x * sigmoidf_(x); }
;     __device__ __forceinline__ void operator()(const f32x4 (&acc)[2][2][4][2], const Unit& u, int wr, int wc, int fr, int fq) const {
;         const int row0 = u.pm * BM + wr * 64 + fr, col0 = u.pn * HALF + wc * 32 + 8 * fq;
;         float rsv[2][4]; load_rstd(rsv, ssq, row0);
; #pragma unroll
;         for (int ai = 0; ai < 2; ++ai)
; #pragma unroll
;             for (int m = 0; m < 4; ++m) { const int row = row0 + ai * HALF + m * 16; bf16_t* rowp = O + (size_t)row * ldc + col0; const float rs = rsv[ai][m];
;                 f32x4 v0, v1;
; #pragma unroll
;                 for (int j = 0; j < 4; ++j) { v0[j] = siluf_(acc[ai][0][m][0][j] * rs) * (acc[ai][1][m][0][j] * rs); v1[j] = siluf_(acc[ai][0][m][1][j] * rs) * (acc[ai][1][m][1][j] * rs); }
;                 u32x4 w; w.x = cvt_pk_bf16(v0[0], v0[1]); w.y = cvt_pk_bf16(v0[2], v0[3]); w.z = cvt_pk_bf16(v1[0], v1[1]); w.w = cvt_pk_bf16(v1[2], v1[3]);
;                 *(u32x4*)rowp = w; }
	v_mul_f32_e32 v107, v229, v107
	v_mfma_f32_16x16x32_bf16 v[24:27], v[154:157], v[212:215], v[24:27]
	v_mul_f32_e32 v104, v108, v104
	v_mul_f32_e32 v105, v109, v105
	v_mul_f32_e32 v106, v110, v106
	v_mul_f32_e32 v107, v111, v107
	v_mul_f32_e32 v96, v173, v96
	v_mul_f32_e32 v97, v173, v97
	v_mul_f32_e32 v98, v173, v98
	v_mul_f32_e32 v99, v173, v99
	v_mul_f32_e32 v100, v173, v100
	v_mul_f32_e32 v101, v173, v101
	v_mfma_f32_16x16x32_bf16 v[16:19], v[162:165], v[212:215], v[16:19]
	v_mul_f32_e32 v102, v173, v102
	v_mul_f32_e32 v103, v173, v103
	v_mul_f32_e32 v224, s100, v96
	v_mul_f32_e32 v225, s101, v97
	v_mul_f32_e32 v228, s100, v98
	v_mul_f32_e32 v229, s101, v99
	v_exp_f32_e32 v224, v224
	v_exp_f32_e32 v225, v225
	v_exp_f32_e32 v228, v228
	v_exp_f32_e32 v229, v229
	v_mfma_f32_16x16x32_bf16 v[8:11], v[154:157], v[240:243], v[8:11]
	v_add_f32_e32 v224, 1.0, v224
	v_add_f32_e32 v225, 1.0, v225
	v_add_f32_e32 v228, 1.0, v228
	v_add_f32_e32 v229, 1.0, v229
	v_rcp_f32_e32 v224, v224
	v_rcp_f32_e32 v225, v225
	v_rcp_f32_e32 v228, v228
	v_rcp_f32_e32 v229, v229
	v_nop
	v_mul_f32_e32 v96, v224, v96
	v_mfma_f32_16x16x32_bf16 v[4:7], v[162:165], v[240:243], v[4:7]
	v_mul_f32_e32 v97, v225, v97
	v_mul_f32_e32 v98, v228, v98
	v_mul_f32_e32 v99, v229, v99
	v_mul_f32_e32 v96, v100, v96
	v_mul_f32_e32 v97, v101, v97
	v_mul_f32_e32 v98, v102, v98
	v_mul_f32_e32 v99, v103, v99
	v_cvt_pk_bf16_f32 v104, v104, v105
	v_cvt_pk_bf16_f32 v105, v106, v107
	v_cvt_pk_bf16_f32 v106, v96, v97
	s_setprio 0
	s_setprio 1
	v_mfma_f32_16x16x32_bf16 v[60:63], v[176:179], v[192:195], v[60:63]
	v_cvt_pk_bf16_f32 v107, v98, v99
	global_store_dwordx4 v[232:233], v[104:107], off
	v_lshl_add_u64 v[232:233], v[232:233], 0, s[98:99]
	v_mul_f32_e32 v88, v236, v88
	v_mul_f32_e32 v89, v236, v89
	v_mul_f32_e32 v90, v236, v90
	v_mul_f32_e32 v91, v236, v91
	v_mul_f32_e32 v92, v236, v92
	v_mul_f32_e32 v93, v236, v93
	v_mul_f32_e32 v94, v236, v94
	v_mfma_f32_16x16x32_bf16 v[52:55], v[184:187], v[192:195], v[52:55]
	v_mul_f32_e32 v95, v236, v95
	v_mul_f32_e32 v224, s100, v88
	v_mul_f32_e32 v225, s101, v89
	v_mul_f32_e32 v228, s100, v90
	v_mul_f32_e32 v229, s101, v91
	v_exp_f32_e32 v224, v224
	v_exp_f32_e32 v225, v225
	v_exp_f32_e32 v228, v228
	v_exp_f32_e32 v229, v229
	v_add_f32_e32 v224, 1.0, v224
	v_mfma_f32_16x16x32_bf16 v[44:47], v[176:179], v[200:203], v[44:47]
	v_add_f32_e32 v225, 1.0, v225
	v_add_f32_e32 v228, 1.0, v228
	v_add_f32_e32 v229, 1.0, v229
	v_rcp_f32_e32 v224, v224
	v_rcp_f32_e32 v225, v225
	v_rcp_f32_e32 v228, v228
	v_rcp_f32_e32 v229, v229
	v_nop
	v_mul_f32_e32 v88, v224, v88
	v_mul_f32_e32 v89, v225, v89
	v_mfma_f32_16x16x32_bf16 v[36:39], v[184:187], v[200:203], v[36:39]
	v_mul_f32_e32 v90, v228, v90
	v_mul_f32_e32 v91, v229, v91
	v_mul_f32_e32 v88, v92, v88
	v_mul_f32_e32 v89, v93, v89
	v_mul_f32_e32 v90, v94, v90
	v_mul_f32_e32 v91, v95, v91
	v_mul_f32_e32 v80, v236, v80
	v_mul_f32_e32 v81, v236, v81
	v_mul_f32_e32 v82, v236, v82
	v_mul_f32_e32 v83, v236, v83
	v_mfma_f32_16x16x32_bf16 v[28:31], v[176:179], v[208:211], v[28:31]
	v_mul_f32_e32 v84, v236, v84
	v_mul_f32_e32 v85, v236, v85
	v_mul_f32_e32 v86, v236, v86
	v_mul_f32_e32 v87, v236, v87
	v_mul_f32_e32 v224, s100, v80
	v_mul_f32_e32 v225, s101, v81
	v_mul_f32_e32 v228, s100, v82
	v_mul_f32_e32 v229, s101, v83
	v_exp_f32_e32 v224, v224
	v_exp_f32_e32 v225, v225
	v_mfma_f32_16x16x32_bf16 v[20:23], v[184:187], v[208:211], v[20:23]
	v_exp_f32_e32 v228, v228
	v_exp_f32_e32 v229, v229
	v_add_f32_e32 v224, 1.0, v224
	v_add_f32_e32 v225, 1.0, v225
	v_add_f32_e32 v228, 1.0, v228
	v_add_f32_e32 v229, 1.0, v229
	v_rcp_f32_e32 v224, v224
	v_rcp_f32_e32 v225, v225
	v_rcp_f32_e32 v228, v228
	v_rcp_f32_e32 v229, v229
	v_mfma_f32_16x16x32_bf16 v[12:15], v[176:179], v[216:219], v[12:15]
	v_nop
	v_mul_f32_e32 v80, v224, v80
; __device__ __forceinline__ unsigned cvt_pk_bf16(float lo, float hi) { unsigned r; asm volatile("v_cvt_pk_bf16_f32 %0, %1, %2" : "=v"(r) : "v"(lo), "v"(hi)); return r; }
; __device__ __forceinline__ float siluf_(float x) { return x * sigmoidf_(x); }
; #define PG8_BAR __builtin_amdgcn_s_barrier()
;     __device__ __forceinline__ void operator()(const f32x4 (&acc)[2][2][4][2], const Unit& u, int wr, int wc, int fr, int fq) const {
;         const int row0 = u.pm * BM + wr * 64 + fr, col0 = u.pn * HALF + wc * 32 + 8 * fq;
;         float rsv[2][4]; load_rstd(rsv, ssq, row0);
; #pragma unroll
;         for (int ai = 0; ai < 2; ++ai)
; #pragma unroll
;             for (int m = 0; m < 4; ++m) { const int row = row0 + ai * HALF + m * 16; bf16_t* rowp = O + (size_t)row * ldc + col0; const float rs = rsv[ai][m];
;                 f32x4 v0, v1;
; #pragma unroll
;                 for (int j = 0; j < 4; ++j) { v0[j] = siluf_(acc[ai][0][m][0][j] * rs) * (acc[ai][1][m][0][j] * rs); v1[j] = siluf_(acc[ai][0][m][1][j] * rs) * (acc[ai][1][m][1][j] * rs); }
;                 u32x4 w; w.x = cvt_pk_bf16(v0[0], v0[1]); w.y = cvt_pk_bf16(v0[2], v0[3]); w.z = cvt_pk_bf16(v1[0], v1[1]); w.w = cvt_pk_bf16(v1[2], v1[3]);
;                 *(u32x4*)rowp = w; }
; template <class Epi, bool ALIGN_EPI>
; __device__ __forceinline__ void gemm_phase(LAS unsigned char* lds, const Gemm g, const StaticOrder& S, const Epi& E, const int tid) {
;     ...
;         if constexpr (ALIGN_EPI) { if (wr == 0) PG8_BAR; }
;         { int t2 = tid; asm volatile("" : "+v"(t2)); const int l2 = t2 & 63, w2 = __builtin_amdgcn_readfirstlane(t2 >> 6); E(acc, cur, w2 >> 2, w2 & 3, l2 & 15, l2 >> 4); }
;         if (!has_next) break;
; #pragma unroll
;         for (int a = 0; a < 2; ++a)
; #pragma unroll
;             for (int b = 0; b < 2; ++b)
; #pragma unroll
;                 for (int m = 0; m < 4; ++m)
; #pragma unroll
;                     for (int n = 0; n < 2; ++n) acc[a][b][m][n] = (f32x4){0.f, 0.f, 0.f, 0.f};
;         cur = nxt; cA = nA; cB = nB; ++ui;
;         if constexpr (ALIGN_EPI) { if (wr == 1) PG8_BAR; }
	v_mul_f32_e32 v81, v225, v81
	v_mul_f32_e32 v82, v228, v82
	v_mul_f32_e32 v83, v229, v83
	v_mul_f32_e32 v80, v84, v80
	v_mul_f32_e32 v81, v85, v81
	v_mul_f32_e32 v82, v86, v82
	v_mul_f32_e32 v83, v87, v83
	v_cvt_pk_bf16_f32 v88, v88, v89
	v_mfma_f32_16x16x32_bf16 v[0:3], v[184:187], v[216:219], v[0:3]
	v_cvt_pk_bf16_f32 v89, v90, v91
	v_cvt_pk_bf16_f32 v90, v80, v81
	v_cvt_pk_bf16_f32 v91, v82, v83
	global_store_dwordx4 v[232:233], v[88:91], off
	v_lshl_add_u64 v[232:233], v[232:233], 0, s[98:99]
	v_mul_f32_e32 v72, v237, v72
	v_mul_f32_e32 v73, v237, v73
	v_mul_f32_e32 v74, v237, v74
	v_mul_f32_e32 v75, v237, v75
	v_mul_f32_e32 v76, v237, v76
	v_mfma_f32_16x16x32_bf16 v[60:63], v[180:183], v[196:199], v[60:63]
	v_mul_f32_e32 v77, v237, v77
	v_mul_f32_e32 v78, v237, v78
	v_mul_f32_e32 v79, v237, v79
	v_mul_f32_e32 v224, s100, v72
	v_mul_f32_e32 v225, s101, v73
	v_mul_f32_e32 v228, s100, v74
	v_mul_f32_e32 v229, s101, v75
	v_exp_f32_e32 v224, v224
	v_exp_f32_e32 v225, v225
	v_exp_f32_e32 v228, v228
	v_mfma_f32_16x16x32_bf16 v[52:55], v[188:191], v[196:199], v[52:55]
	v_exp_f32_e32 v229, v229
	v_add_f32_e32 v224, 1.0, v224
	v_add_f32_e32 v225, 1.0, v225
	v_add_f32_e32 v228, 1.0, v228
	v_add_f32_e32 v229, 1.0, v229
	v_rcp_f32_e32 v224, v224
	v_rcp_f32_e32 v225, v225
	v_rcp_f32_e32 v228, v228
	v_rcp_f32_e32 v229, v229
	v_nop
	v_mfma_f32_16x16x32_bf16 v[44:47], v[180:183], v[204:207], v[44:47]
	v_mul_f32_e32 v72, v224, v72
	v_mul_f32_e32 v73, v225, v73
	v_mul_f32_e32 v74, v228, v74
	v_mul_f32_e32 v75, v229, v75
	v_mul_f32_e32 v72, v76, v72
	v_mul_f32_e32 v73, v77, v73
	v_mul_f32_e32 v74, v78, v74
	v_mul_f32_e32 v75, v79, v75
	v_mul_f32_e32 v64, v237, v64
	v_mul_f32_e32 v65, v237, v65
	v_mfma_f32_16x16x32_bf16 v[36:39], v[188:191], v[204:207], v[36:39]
	v_mul_f32_e32 v66, v237, v66
	v_mul_f32_e32 v67, v237, v67
	v_mul_f32_e32 v68, v237, v68
	v_mul_f32_e32 v69, v237, v69
	v_mul_f32_e32 v70, v237, v70
	v_mul_f32_e32 v71, v237, v71
	v_mul_f32_e32 v224, s100, v64
	v_mul_f32_e32 v225, s101, v65
	v_mul_f32_e32 v228, s100, v66
	v_mul_f32_e32 v229, s101, v67
	v_mfma_f32_16x16x32_bf16 v[28:31], v[180:183], v[212:215], v[28:31]
	v_exp_f32_e32 v224, v224
	v_exp_f32_e32 v225, v225
	v_exp_f32_e32 v228, v228
	v_exp_f32_e32 v229, v229
	v_add_f32_e32 v224, 1.0, v224
	v_add_f32_e32 v225, 1.0, v225
	v_add_f32_e32 v228, 1.0, v228
	v_add_f32_e32 v229, 1.0, v229
	v_rcp_f32_e32 v224, v224
	v_rcp_f32_e32 v225, v225
	v_mfma_f32_16x16x32_bf16 v[20:23], v[188:191], v[212:215], v[20:23]
	v_rcp_f32_e32 v228, v228
	v_rcp_f32_e32 v229, v229
	v_nop
	v_mul_f32_e32 v64, v224, v64
	v_mul_f32_e32 v65, v225, v65
	v_mul_f32_e32 v66, v228, v66
	v_mul_f32_e32 v67, v229, v67
	v_mul_f32_e32 v64, v68, v64
	v_mul_f32_e32 v65, v69, v65
	v_mul_f32_e32 v66, v70, v66
	v_mfma_f32_16x16x32_bf16 v[12:15], v[180:183], v[240:243], v[12:15]
	v_mul_f32_e32 v67, v71, v67
	v_cvt_pk_bf16_f32 v72, v72, v73
	v_cvt_pk_bf16_f32 v73, v74, v75
	v_cvt_pk_bf16_f32 v74, v64, v65
	v_cvt_pk_bf16_f32 v75, v66, v67
	global_store_dwordx4 v[232:233], v[72:75], off
	v_lshl_add_u64 v[232:233], v[232:233], 0, s[98:99]
	v_lshl_add_u64 v[232:233], v[232:233], 0, s[98:99]
	v_lshl_add_u64 v[232:233], v[232:233], 0, s[98:99]
	v_lshl_add_u64 v[232:233], v[232:233], 0, s[98:99]
	v_mfma_f32_16x16x32_bf16 v[0:3], v[188:191], v[240:243], v[0:3]
	v_lshl_add_u64 v[232:233], v[232:233], 0, s[98:99]
	s_setprio 0
	s_barrier
	v_lshl_add_u64 v[142:143], v[142:143], 0, s[80:81]
	v_lshl_add_u64 v[144:145], v[144:145], 0, s[80:81]
	s_and_b64 vcc, exec, s[8:9]
	s_cbranch_vccnz .Lgu_notdefer
	s_cmp_lg_u32 s62, s64
	s_cbranch_scc1 .Lgu_notdefer
	s_mov_b32 s101, 1
	s_mov_b32 s63, s61
	s_mov_b32 s64, s62
	v_mov_b64_e32 v[144:145], v[140:141]
	v_mov_b64_e32 v[142:143], v[138:139]
	s_branch .LBB0_300
.Lgu_notdefer:
	s_mov_b32 s101, 0

; __device__ __forceinline__ unsigned cvt_pk_bf16(float lo, float hi) { unsigned r; asm volatile("v_cvt_pk_bf16_f32 %0, %1, %2" : "=v"(r) : "v"(lo), "v"(hi)); return r; }
; __device__ __forceinline__ float siluf_(float x) { return x * sigmoidf_(x); }
;     __device__ __forceinline__ void operator()(const f32x4 (&acc)[2][2][4][2], const Unit& u, int wr, int wc, int fr, int fq) const {
;         const int row0 = u.pm * BM + wr * 64 + fr, col0 = u.pn * HALF + wc * 32 + 8 * fq;
;         float rsv[2][4]; load_rstd(rsv, ssq, row0);
; #pragma unroll
;         for (int ai = 0; ai < 2; ++ai)
; #pragma unroll
;             for (int m = 0; m < 4; ++m) { const int row = row0 + ai * HALF + m * 16; bf16_t* rowp = O + (size_t)row * ldc + col0; const float rs = rsv[ai][m];
;                 f32x4 v0, v1;
; #pragma unroll
;                 for (int j = 0; j < 4; ++j) { v0[j] = siluf_(acc[ai][0][m][0][j] * rs) * (acc[ai][1][m][0][j] * rs); v1[j] = siluf_(acc[ai][0][m][1][j] * rs) * (acc[ai][1][m][1][j] * rs); }
;                 u32x4 w; w.x = cvt_pk_bf16(v0[0], v0[1]); w.y = cvt_pk_bf16(v0[2], v0[3]); w.z = cvt_pk_bf16(v1[0], v1[1]); w.w = cvt_pk_bf16(v1[2], v1[3]);
;                 *(u32x4*)rowp = w; }
.LBB0_311:
	s_nop 15
	s_nop 15
	s_lshl_b32 s98, s28, 5
	s_mov_b32 s99, 0
	s_mov_b32 s100, 0xbfb8aa3b
	s_mov_b32 s101, 0xbfb8aa3b
	v_pk_mul_f32 v[56:57], v[56:57], v[238:239] op_sel_hi:[1,0]
	v_pk_mul_f32 v[58:59], v[58:59], v[238:239] op_sel_hi:[1,0]
	v_pk_mul_f32 v[60:61], v[60:61], v[238:239] op_sel_hi:[1,0]
	v_pk_mul_f32 v[62:63], v[62:63], v[238:239] op_sel_hi:[1,0]
	v_pk_mul_f32 v[224:225], v[56:57], s[100:101]
	v_pk_mul_f32 v[228:229], v[58:59], s[100:101]
	v_exp_f32_e32 v224, v224
	v_exp_f32_e32 v225, v225
	v_exp_f32_e32 v228, v228
	v_exp_f32_e32 v229, v229
	v_add_f32_e32 v224, 1.0, v224
	v_add_f32_e32 v225, 1.0, v225
	v_add_f32_e32 v228, 1.0, v228
	v_add_f32_e32 v229, 1.0, v229
	v_rcp_f32_e32 v224, v224
	v_rcp_f32_e32 v225, v225
	v_rcp_f32_e32 v228, v228
	v_rcp_f32_e32 v229, v229
	v_nop
	v_pk_mul_f32 v[56:57], v[56:57], v[224:225]
	v_pk_mul_f32 v[58:59], v[58:59], v[228:229]
	v_pk_mul_f32 v[56:57], v[56:57], v[60:61]
	v_pk_mul_f32 v[58:59], v[58:59], v[62:63]
	v_pk_mul_f32 v[48:49], v[48:49], v[238:239] op_sel_hi:[1,0]
	v_pk_mul_f32 v[50:51], v[50:51], v[238:239] op_sel_hi:[1,0]
	v_pk_mul_f32 v[52:53], v[52:53], v[238:239] op_sel_hi:[1,0]
	v_pk_mul_f32 v[54:55], v[54:55], v[238:239] op_sel_hi:[1,0]
	v_pk_mul_f32 v[224:225], v[48:49], s[100:101]
	v_pk_mul_f32 v[228:229], v[50:51], s[100:101]
	v_exp_f32_e32 v224, v224
	v_exp_f32_e32 v225, v225
	v_exp_f32_e32 v228, v228
	v_exp_f32_e32 v229, v229
	v_add_f32_e32 v224, 1.0, v224
	v_add_f32_e32 v225, 1.0, v225
	v_add_f32_e32 v228, 1.0, v228
	v_add_f32_e32 v229, 1.0, v229
	v_rcp_f32_e32 v224, v224
	v_rcp_f32_e32 v225, v225
	v_rcp_f32_e32 v228, v228
	v_rcp_f32_e32 v229, v229
	v_nop
	v_pk_mul_f32 v[48:49], v[48:49], v[224:225]
	v_pk_mul_f32 v[50:51], v[50:51], v[228:229]
	v_pk_mul_f32 v[48:49], v[48:49], v[52:53]
	v_pk_mul_f32 v[50:51], v[50:51], v[54:55]
	v_cvt_pk_bf16_f32 v56, v56, v57
	v_cvt_pk_bf16_f32 v57, v58, v59
	v_cvt_pk_bf16_f32 v58, v48, v49
	v_cvt_pk_bf16_f32 v59, v50, v51
	global_store_dwordx4 v[232:233], v[56:59], off
	v_lshl_add_u64 v[232:233], v[232:233], 0, s[98:99]
	v_pk_mul_f32 v[40:41], v[40:41], v[238:239] op_sel:[0,1]
	v_pk_mul_f32 v[42:43], v[42:43], v[238:239] op_sel:[0,1]
	v_pk_mul_f32 v[44:45], v[44:45], v[238:239] op_sel:[0,1]
	v_pk_mul_f32 v[46:47], v[46:47], v[238:239] op_sel:[0,1]
	v_pk_mul_f32 v[224:225], v[40:41], s[100:101]
	v_pk_mul_f32 v[228:229], v[42:43], s[100:101]
	v_exp_f32_e32 v224, v224
	v_exp_f32_e32 v225, v225
	v_exp_f32_e32 v228, v228
	v_exp_f32_e32 v229, v229
	v_add_f32_e32 v224, 1.0, v224
	v_add_f32_e32 v225, 1.0, v225
	v_add_f32_e32 v228, 1.0, v228
	v_add_f32_e32 v229, 1.0, v229
	v_rcp_f32_e32 v224, v224
	v_rcp_f32_e32 v225, v225
	v_rcp_f32_e32 v228, v228
	v_rcp_f32_e32 v229, v229
	v_nop
	v_pk_mul_f32 v[40:41], v[40:41], v[224:225]
	v_pk_mul_f32 v[42:43], v[42:43], v[228:229]
	v_pk_mul_f32 v[40:41], v[40:41], v[44:45]
	v_pk_mul_f32 v[42:43], v[42:43], v[46:47]
	v_pk_mul_f32 v[32:33], v[32:33], v[238:239] op_sel:[0,1]
	v_pk_mul_f32 v[34:35], v[34:35], v[238:239] op_sel:[0,1]
	v_pk_mul_f32 v[36:37], v[36:37], v[238:239] op_sel:[0,1]
	v_pk_mul_f32 v[38:39], v[38:39], v[238:239] op_sel:[0,1]
	v_pk_mul_f32 v[224:225], v[32:33], s[100:101]
	v_pk_mul_f32 v[228:229], v[34:35], s[100:101]
	v_exp_f32_e32 v224, v224
	v_exp_f32_e32 v225, v225
	v_exp_f32_e32 v228, v228
	v_exp_f32_e32 v229, v229
	v_add_f32_e32 v224, 1.0, v224
	v_add_f32_e32 v225, 1.0, v225
	v_add_f32_e32 v228, 1.0, v228
	v_add_f32_e32 v229, 1.0, v229
	v_rcp_f32_e32 v224, v224
	v_rcp_f32_e32 v225, v225
	v_rcp_f32_e32 v228, v228
	v_rcp_f32_e32 v229, v229
	v_nop
	v_pk_mul_f32 v[32:33], v[32:33], v[224:225]
	v_pk_mul_f32 v[34:35], v[34:35], v[228:229]
	v_pk_mul_f32 v[32:33], v[32:33], v[36:37]
	v_pk_mul_f32 v[34:35], v[34:35], v[38:39]
	v_cvt_pk_bf16_f32 v40, v40, v41
	v_cvt_pk_bf16_f32 v41, v42, v43
	v_cvt_pk_bf16_f32 v42, v32, v33
	v_cvt_pk_bf16_f32 v43, v34, v35
	global_store_dwordx4 v[232:233], v[40:43], off
; __device__ __forceinline__ unsigned cvt_pk_bf16(float lo, float hi) { unsigned r; asm volatile("v_cvt_pk_bf16_f32 %0, %1, %2" : "=v"(r) : "v"(lo), "v"(hi)); return r; }
; __device__ __forceinline__ float siluf_(float x) { return x * sigmoidf_(x); }
; #define PG8_BAR __builtin_amdgcn_s_barrier()
;     __device__ __forceinline__ void operator()(const f32x4 (&acc)[2][2][4][2], const Unit& u, int wr, int wc, int fr, int fq) const {
;         const int row0 = u.pm * BM + wr * 64 + fr, col0 = u.pn * HALF + wc * 32 + 8 * fq;
;         float rsv[2][4]; load_rstd(rsv, ssq, row0);
; #pragma unroll
;         for (int ai = 0; ai < 2; ++ai)
; #pragma unroll
;             for (int m = 0; m < 4; ++m) { const int row = row0 + ai * HALF + m * 16; bf16_t* rowp = O + (size_t)row * ldc + col0; const float rs = rsv[ai][m];
;                 f32x4 v0, v1;
; #pragma unroll
;                 for (int j = 0; j < 4; ++j) { v0[j] = siluf_(acc[ai][0][m][0][j] * rs) * (acc[ai][1][m][0][j] * rs); v1[j] = siluf_(acc[ai][0][m][1][j] * rs) * (acc[ai][1][m][1][j] * rs); }
;                 u32x4 w; w.x = cvt_pk_bf16(v0[0], v0[1]); w.y = cvt_pk_bf16(v0[2], v0[3]); w.z = cvt_pk_bf16(v1[0], v1[1]); w.w = cvt_pk_bf16(v1[2], v1[3]);
;                 *(u32x4*)rowp = w; }
; template <class Epi, bool ALIGN_EPI>
; __device__ __forceinline__ void gemm_phase(LAS unsigned char* lds, const Gemm g, const StaticOrder& S, const Epi& E, const int tid) {
;     ...
;         if (!has_next) break;
; #pragma unroll
;         for (int a = 0; a < 2; ++a)
; #pragma unroll
;             for (int b = 0; b < 2; ++b)
; #pragma unroll
;                 for (int m = 0; m < 4; ++m)
; #pragma unroll
;                     for (int n = 0; n < 2; ++n) acc[a][b][m][n] = (f32x4){0.f, 0.f, 0.f, 0.f};
;         cur = nxt; cA = nA; cB = nB; ++ui;
;         if constexpr (ALIGN_EPI) { if (wr == 1) PG8_BAR; }
;     }
	v_lshl_add_u64 v[232:233], v[232:233], 0, s[98:99]
	v_pk_mul_f32 v[24:25], v[24:25], v[230:231] op_sel_hi:[1,0]
	v_pk_mul_f32 v[26:27], v[26:27], v[230:231] op_sel_hi:[1,0]
	v_pk_mul_f32 v[28:29], v[28:29], v[230:231] op_sel_hi:[1,0]
	v_pk_mul_f32 v[30:31], v[30:31], v[230:231] op_sel_hi:[1,0]
	v_pk_mul_f32 v[224:225], v[24:25], s[100:101]
	v_pk_mul_f32 v[228:229], v[26:27], s[100:101]
	v_exp_f32_e32 v224, v224
	v_exp_f32_e32 v225, v225
	v_exp_f32_e32 v228, v228
	v_exp_f32_e32 v229, v229
	v_add_f32_e32 v224, 1.0, v224
	v_add_f32_e32 v225, 1.0, v225
	v_add_f32_e32 v228, 1.0, v228
	v_add_f32_e32 v229, 1.0, v229
	v_rcp_f32_e32 v224, v224
	v_rcp_f32_e32 v225, v225
	v_rcp_f32_e32 v228, v228
	v_rcp_f32_e32 v229, v229
	v_nop
	v_pk_mul_f32 v[24:25], v[24:25], v[224:225]
	v_pk_mul_f32 v[26:27], v[26:27], v[228:229]
	v_pk_mul_f32 v[24:25], v[24:25], v[28:29]
	v_pk_mul_f32 v[26:27], v[26:27], v[30:31]
	v_pk_mul_f32 v[16:17], v[16:17], v[230:231] op_sel_hi:[1,0]
	v_pk_mul_f32 v[18:19], v[18:19], v[230:231] op_sel_hi:[1,0]
	v_pk_mul_f32 v[20:21], v[20:21], v[230:231] op_sel_hi:[1,0]
	v_pk_mul_f32 v[22:23], v[22:23], v[230:231] op_sel_hi:[1,0]
	v_pk_mul_f32 v[224:225], v[16:17], s[100:101]
	v_pk_mul_f32 v[228:229], v[18:19], s[100:101]
	v_exp_f32_e32 v224, v224
	v_exp_f32_e32 v225, v225
	v_exp_f32_e32 v228, v228
	v_exp_f32_e32 v229, v229
	v_add_f32_e32 v224, 1.0, v224
	v_add_f32_e32 v225, 1.0, v225
	v_add_f32_e32 v228, 1.0, v228
	v_add_f32_e32 v229, 1.0, v229
	v_rcp_f32_e32 v224, v224
	v_rcp_f32_e32 v225, v225
	v_rcp_f32_e32 v228, v228
	v_rcp_f32_e32 v229, v229
	v_nop
	v_pk_mul_f32 v[16:17], v[16:17], v[224:225]
	v_pk_mul_f32 v[18:19], v[18:19], v[228:229]
	v_pk_mul_f32 v[16:17], v[16:17], v[20:21]
	v_pk_mul_f32 v[18:19], v[18:19], v[22:23]
	v_cvt_pk_bf16_f32 v24, v24, v25
	v_cvt_pk_bf16_f32 v25, v26, v27
	v_cvt_pk_bf16_f32 v26, v16, v17
	v_cvt_pk_bf16_f32 v27, v18, v19
	global_store_dwordx4 v[232:233], v[24:27], off
	v_lshl_add_u64 v[232:233], v[232:233], 0, s[98:99]
	v_pk_mul_f32 v[8:9], v[8:9], v[230:231] op_sel:[0,1]
	v_pk_mul_f32 v[10:11], v[10:11], v[230:231] op_sel:[0,1]
	v_pk_mul_f32 v[12:13], v[12:13], v[230:231] op_sel:[0,1]
	v_pk_mul_f32 v[14:15], v[14:15], v[230:231] op_sel:[0,1]
	v_pk_mul_f32 v[224:225], v[8:9], s[100:101]
	v_pk_mul_f32 v[228:229], v[10:11], s[100:101]
	v_exp_f32_e32 v224, v224
	v_exp_f32_e32 v225, v225
	v_exp_f32_e32 v228, v228
	v_exp_f32_e32 v229, v229
	v_add_f32_e32 v224, 1.0, v224
	v_add_f32_e32 v225, 1.0, v225
	v_add_f32_e32 v228, 1.0, v228
	v_add_f32_e32 v229, 1.0, v229
	v_rcp_f32_e32 v224, v224
	v_rcp_f32_e32 v225, v225
	v_rcp_f32_e32 v228, v228
	v_rcp_f32_e32 v229, v229
	v_nop
	v_pk_mul_f32 v[8:9], v[8:9], v[224:225]
	v_pk_mul_f32 v[10:11], v[10:11], v[228:229]
	v_pk_mul_f32 v[8:9], v[8:9], v[12:13]
	v_pk_mul_f32 v[10:11], v[10:11], v[14:15]
	v_pk_mul_f32 v[4:5], v[4:5], v[230:231] op_sel:[0,1]
	v_pk_mul_f32 v[6:7], v[6:7], v[230:231] op_sel:[0,1]
	v_pk_mul_f32 v[0:1], v[0:1], v[230:231] op_sel:[0,1]
	v_pk_mul_f32 v[2:3], v[2:3], v[230:231] op_sel:[0,1]
	v_pk_mul_f32 v[224:225], v[4:5], s[100:101]
	v_pk_mul_f32 v[228:229], v[6:7], s[100:101]
	v_exp_f32_e32 v224, v224
	v_exp_f32_e32 v225, v225
	v_exp_f32_e32 v228, v228
	v_exp_f32_e32 v229, v229
	v_add_f32_e32 v224, 1.0, v224
	v_add_f32_e32 v225, 1.0, v225
	v_add_f32_e32 v228, 1.0, v228
	v_add_f32_e32 v229, 1.0, v229
	v_rcp_f32_e32 v224, v224
	v_rcp_f32_e32 v225, v225
	v_rcp_f32_e32 v228, v228
	v_rcp_f32_e32 v229, v229
	v_nop
	v_pk_mul_f32 v[4:5], v[4:5], v[224:225]
	v_pk_mul_f32 v[6:7], v[6:7], v[228:229]
	v_pk_mul_f32 v[4:5], v[4:5], v[0:1]
	v_pk_mul_f32 v[6:7], v[6:7], v[2:3]
	v_cvt_pk_bf16_f32 v8, v8, v9
	v_cvt_pk_bf16_f32 v9, v10, v11
	v_cvt_pk_bf16_f32 v10, v4, v5
	v_cvt_pk_bf16_f32 v11, v6, v7
	global_store_dwordx4 v[232:233], v[8:11], off
	s_mov_b32 s101, 0
	s_mov_b64 s[10:11], -1
	s_and_b64 vcc, exec, s[8:9]
	s_cbranch_vccnz .LBB0_299
	s_andn2_b64 vcc, exec, s[40:41]
	s_cbranch_vccnz .LBB0_298
	s_barrier
	s_branch .LBB0_298
